# v10 + pool epilogue loads batched + up-proj epilogue ssq preloads
# speedup vs baseline: 1.0072x; 1.0072x over previous
; __device__ __forceinline__ u32x4 pack8(f32x4 a, f32x4 b) { u32x4 o; o.x = cvtpk(a[0], a[1]); o.y = cvtpk(a[2], a[3]); o.z = cvtpk(b[0], b[1]); o.w = cvtpk(b[2], b[3]); return o; }
;     template <int KIND> __device__ __forceinline__ void run(f32x4 (&acc)[2][2][4][2], const GUnit& u, int wr, int wc, int fr, int fq, int tid) const {
;     ...
;                 } else if (kind == EP_KV) {
;                     const float rs = __builtin_amdgcn_rsqf(ssq_kv[row] * (1.f / 128.f) + EPS);
; #pragma unroll
;                     for (int bj = 0; bj < 2; ++bj)
;                         *(u32x4*)(KVb + (size_t)row * 1024 + pn * 256 + bj * 128 + wc * 32 + 8 * fq) = pack8(acc[ai][bj][m][0] * rs, acc[ai][bj][m][1] * rs);
.LBB0_457:
	s_and_b64 vcc, exec, s[2:3]
	s_cbranch_vccz .LBB0_459
	v_mov_b32_e32 v0, v189
	s_lshl_b32 s14, s42, 8
	v_add_u32_e32 v130, s14, v196
	v_readlane_b32 s44, v252, 9
	v_ashrrev_i32_e32 v131, 31, v130
	v_readlane_b32 s45, v252, 10
	s_lshl_b32 s2, s28, 8
	v_readlane_b32 s16, v255, 3
	v_lshl_add_u64 v[132:133], v[130:131], 2, s[44:45]
	global_load_dword v0, v[132:133], off
	v_add_u32_e32 v222, s14, v198
	v_ashrrev_i32_e32 v223, 31, v222
	v_lshl_add_u64 v[222:223], v[222:223], 2, s[44:45]
	global_load_dword v214, v[222:223], off
	v_add_u32_e32 v222, s14, v199
	v_ashrrev_i32_e32 v223, 31, v222
	v_lshl_add_u64 v[222:223], v[222:223], 2, s[44:45]
	global_load_dword v215, v[222:223], off
	v_add_u32_e32 v222, s14, v200
	v_ashrrev_i32_e32 v223, 31, v222
	v_lshl_add_u64 v[222:223], v[222:223], 2, s[44:45]
	global_load_dword v216, v[222:223], off
	v_add_u32_e32 v222, s14, v201
	v_ashrrev_i32_e32 v223, 31, v222
	v_lshl_add_u64 v[222:223], v[222:223], 2, s[44:45]
	global_load_dword v217, v[222:223], off
	v_add_u32_e32 v222, s14, v206
	v_ashrrev_i32_e32 v223, 31, v222
	v_lshl_add_u64 v[222:223], v[222:223], 2, s[44:45]
	global_load_dword v218, v[222:223], off
	v_add_u32_e32 v222, s14, v207
	v_ashrrev_i32_e32 v223, 31, v222
	v_lshl_add_u64 v[222:223], v[222:223], 2, s[44:45]
	global_load_dword v219, v[222:223], off
	v_add_u32_e32 v222, s14, v208
	v_ashrrev_i32_e32 v223, 31, v222
	v_lshl_add_u64 v[222:223], v[222:223], 2, s[44:45]
	global_load_dword v220, v[222:223], off
	s_ashr_i32 s3, s2, 31
	v_lshlrev_b64 v[136:137], 11, v[130:131]
	v_readlane_b32 s17, v255, 4
	s_lshl_b64 s[2:3], s[2:3], 1
	s_lshl_b32 s8, s85, 1
	v_lshl_add_u64 v[136:137], s[16:17], 0, v[136:137]
	v_lshl_add_u64 v[136:137], v[136:137], 0, s[2:3]
	v_lshl_add_u64 v[136:137], v[136:137], 0, s[8:9]
	s_waitcnt vmcnt(0)
	v_fmamk_f32 v0, v0, 0x3c000000, v202
	v_rsq_f32_e32 v134, v0
	v_lshlrev_b32_e32 v0, 1, v188
	v_lshl_add_u64 v[136:137], v[136:137], 0, v[0:1]
	v_pk_mul_f32 v[132:133], v[128:129], v[134:135] op_sel_hi:[1,0]
	v_pk_mul_f32 v[130:131], v[126:127], v[134:135] op_sel_hi:[1,0]
	v_pk_mul_f32 v[138:139], v[124:125], v[134:135] op_sel_hi:[1,0]
	v_pk_mul_f32 v[140:141], v[122:123], v[134:135] op_sel_hi:[1,0]
	v_cvt_pk_bf16_f32 v130, v130, v131
	v_cvt_pk_bf16_f32 v131, v132, v133
	v_cvt_pk_bf16_f32 v132, v140, v141
	v_cvt_pk_bf16_f32 v133, v138, v139
	global_store_dwordx4 v[136:137], v[130:133], off
	v_pk_mul_f32 v[138:139], v[92:93], v[134:135] op_sel_hi:[1,0]
	s_nop 0
	v_pk_mul_f32 v[132:133], v[96:97], v[134:135] op_sel_hi:[1,0]
	v_pk_mul_f32 v[130:131], v[94:95], v[134:135] op_sel_hi:[1,0]
	v_pk_mul_f32 v[134:135], v[90:91], v[134:135] op_sel_hi:[1,0]
	v_cvt_pk_bf16_f32 v130, v130, v131
	v_cvt_pk_bf16_f32 v131, v132, v133
	v_cvt_pk_bf16_f32 v132, v134, v135
	v_cvt_pk_bf16_f32 v133, v138, v139
	global_store_dwordx4 v[136:137], v[130:133], off offset:256
	s_nop 1
	v_add_u32_e32 v130, s14, v198
	v_ashrrev_i32_e32 v131, 31, v130
	v_lshl_add_u64 v[132:133], v[130:131], 2, s[44:45]
	v_mov_b32_e32 v132, v214
	v_lshlrev_b64 v[136:137], 11, v[130:131]
	v_lshl_add_u64 v[136:137], s[16:17], 0, v[136:137]
	v_lshl_add_u64 v[136:137], v[136:137], 0, s[2:3]
	v_lshl_add_u64 v[136:137], v[136:137], 0, s[8:9]
	v_lshl_add_u64 v[136:137], v[136:137], 0, v[0:1]
	s_nop 0
	v_fmamk_f32 v132, v132, 0x3c000000, v202
	v_rsq_f32_e32 v134, v132
	s_nop 0
	v_pk_mul_f32 v[132:133], v[120:121], v[134:135] op_sel_hi:[1,0]
	v_pk_mul_f32 v[130:131], v[118:119], v[134:135] op_sel_hi:[1,0]
	v_pk_mul_f32 v[138:139], v[116:117], v[134:135] op_sel_hi:[1,0]
	v_pk_mul_f32 v[140:141], v[114:115], v[134:135] op_sel_hi:[1,0]
	v_cvt_pk_bf16_f32 v130, v130, v131
	v_cvt_pk_bf16_f32 v131, v132, v133
	v_cvt_pk_bf16_f32 v132, v140, v141
	v_cvt_pk_bf16_f32 v133, v138, v139
	global_store_dwordx4 v[136:137], v[130:133], off
	v_pk_mul_f32 v[138:139], v[84:85], v[134:135] op_sel_hi:[1,0]
	s_nop 0
	v_pk_mul_f32 v[132:133], v[88:89], v[134:135] op_sel_hi:[1,0]
	v_pk_mul_f32 v[130:131], v[86:87], v[134:135] op_sel_hi:[1,0]
	v_pk_mul_f32 v[134:135], v[82:83], v[134:135] op_sel_hi:[1,0]
	v_cvt_pk_bf16_f32 v130, v130, v131
	v_cvt_pk_bf16_f32 v131, v132, v133
	v_cvt_pk_bf16_f32 v132, v134, v135
	v_cvt_pk_bf16_f32 v133, v138, v139
	global_store_dwordx4 v[136:137], v[130:133], off offset:256
	s_nop 1
	v_add_u32_e32 v130, s14, v199
	v_ashrrev_i32_e32 v131, 31, v130
	v_lshl_add_u64 v[132:133], v[130:131], 2, s[44:45]
	v_mov_b32_e32 v132, v215
	v_lshlrev_b64 v[136:137], 11, v[130:131]
	v_lshl_add_u64 v[136:137], s[16:17], 0, v[136:137]
	v_lshl_add_u64 v[136:137], v[136:137], 0, s[2:3]
	v_lshl_add_u64 v[136:137], v[136:137], 0, s[8:9]
	v_lshl_add_u64 v[136:137], v[136:137], 0, v[0:1]
	s_nop 0
	v_fmamk_f32 v132, v132, 0x3c000000, v202
	v_rsq_f32_e32 v134, v132
	s_nop 0
	v_pk_mul_f32 v[132:133], v[112:113], v[134:135] op_sel_hi:[1,0]
	v_pk_mul_f32 v[130:131], v[110:111], v[134:135] op_sel_hi:[1,0]
	v_pk_mul_f32 v[138:139], v[108:109], v[134:135] op_sel_hi:[1,0]
	v_pk_mul_f32 v[140:141], v[106:107], v[134:135] op_sel_hi:[1,0]
	v_cvt_pk_bf16_f32 v130, v130, v131
	v_cvt_pk_bf16_f32 v131, v132, v133
	v_cvt_pk_bf16_f32 v132, v140, v141
	v_cvt_pk_bf16_f32 v133, v138, v139
	global_store_dwordx4 v[136:137], v[130:133], off
	v_pk_mul_f32 v[138:139], v[76:77], v[134:135] op_sel_hi:[1,0]
	s_nop 0
	v_pk_mul_f32 v[132:133], v[80:81], v[134:135] op_sel_hi:[1,0]
	v_pk_mul_f32 v[130:131], v[78:79], v[134:135] op_sel_hi:[1,0]
	v_pk_mul_f32 v[134:135], v[74:75], v[134:135] op_sel_hi:[1,0]
	v_cvt_pk_bf16_f32 v130, v130, v131
	v_cvt_pk_bf16_f32 v131, v132, v133
	v_cvt_pk_bf16_f32 v132, v134, v135
	v_cvt_pk_bf16_f32 v133, v138, v139
; __device__ __forceinline__ u32x4 pack8(f32x4 a, f32x4 b) { u32x4 o; o.x = cvtpk(a[0], a[1]); o.y = cvtpk(a[2], a[3]); o.z = cvtpk(b[0], b[1]); o.w = cvtpk(b[2], b[3]); return o; }
;     template <int KIND> __device__ __forceinline__ void run(f32x4 (&acc)[2][2][4][2], const GUnit& u, int wr, int wc, int fr, int fq, int tid) const {
;     ...
;                 } else if (kind == EP_KV) {
;                     const float rs = __builtin_amdgcn_rsqf(ssq_kv[row] * (1.f / 128.f) + EPS);
; #pragma unroll
;                     for (int bj = 0; bj < 2; ++bj)
;                         *(u32x4*)(KVb + (size_t)row * 1024 + pn * 256 + bj * 128 + wc * 32 + 8 * fq) = pack8(acc[ai][bj][m][0] * rs, acc[ai][bj][m][1] * rs);
	global_store_dwordx4 v[136:137], v[130:133], off offset:256
	s_nop 1
	v_add_u32_e32 v130, s14, v200
	v_ashrrev_i32_e32 v131, 31, v130
	v_lshl_add_u64 v[132:133], v[130:131], 2, s[44:45]
	v_mov_b32_e32 v132, v216
	v_lshlrev_b64 v[136:137], 11, v[130:131]
	v_lshl_add_u64 v[136:137], s[16:17], 0, v[136:137]
	v_lshl_add_u64 v[136:137], v[136:137], 0, s[2:3]
	v_lshl_add_u64 v[136:137], v[136:137], 0, s[8:9]
	v_lshl_add_u64 v[136:137], v[136:137], 0, v[0:1]
	s_nop 0
	v_fmamk_f32 v132, v132, 0x3c000000, v202
	v_rsq_f32_e32 v134, v132
	s_nop 0
	v_pk_mul_f32 v[132:133], v[104:105], v[134:135] op_sel_hi:[1,0]
	v_pk_mul_f32 v[130:131], v[102:103], v[134:135] op_sel_hi:[1,0]
	v_pk_mul_f32 v[138:139], v[100:101], v[134:135] op_sel_hi:[1,0]
	v_pk_mul_f32 v[140:141], v[98:99], v[134:135] op_sel_hi:[1,0]
	v_cvt_pk_bf16_f32 v130, v130, v131
	v_cvt_pk_bf16_f32 v131, v132, v133
	v_cvt_pk_bf16_f32 v132, v140, v141
	v_cvt_pk_bf16_f32 v133, v138, v139
	global_store_dwordx4 v[136:137], v[130:133], off
	v_pk_mul_f32 v[138:139], v[68:69], v[134:135] op_sel_hi:[1,0]
	s_nop 0
	v_pk_mul_f32 v[132:133], v[72:73], v[134:135] op_sel_hi:[1,0]
	v_pk_mul_f32 v[130:131], v[70:71], v[134:135] op_sel_hi:[1,0]
	v_pk_mul_f32 v[134:135], v[66:67], v[134:135] op_sel_hi:[1,0]
	v_cvt_pk_bf16_f32 v130, v130, v131
	v_cvt_pk_bf16_f32 v131, v132, v133
	v_cvt_pk_bf16_f32 v132, v134, v135
	v_cvt_pk_bf16_f32 v133, v138, v139
	global_store_dwordx4 v[136:137], v[130:133], off offset:256
	s_nop 1
	v_add_u32_e32 v130, s14, v201
	v_ashrrev_i32_e32 v131, 31, v130
	v_lshl_add_u64 v[132:133], v[130:131], 2, s[44:45]
	v_mov_b32_e32 v132, v217
	v_lshlrev_b64 v[136:137], 11, v[130:131]
	v_lshl_add_u64 v[136:137], s[16:17], 0, v[136:137]
	v_lshl_add_u64 v[136:137], v[136:137], 0, s[2:3]
	v_lshl_add_u64 v[136:137], v[136:137], 0, s[8:9]
	v_lshl_add_u64 v[136:137], v[136:137], 0, v[0:1]
	s_nop 0
	v_fmamk_f32 v132, v132, 0x3c000000, v202
	v_rsq_f32_e32 v134, v132
	s_nop 0
	v_pk_mul_f32 v[132:133], v[64:65], v[134:135] op_sel_hi:[1,0]
	v_pk_mul_f32 v[130:131], v[62:63], v[134:135] op_sel_hi:[1,0]
	v_pk_mul_f32 v[138:139], v[60:61], v[134:135] op_sel_hi:[1,0]
	v_pk_mul_f32 v[140:141], v[58:59], v[134:135] op_sel_hi:[1,0]
	v_cvt_pk_bf16_f32 v130, v130, v131
	v_cvt_pk_bf16_f32 v131, v132, v133
	v_cvt_pk_bf16_f32 v132, v140, v141
	v_cvt_pk_bf16_f32 v133, v138, v139
	global_store_dwordx4 v[136:137], v[130:133], off
	v_pk_mul_f32 v[138:139], v[28:29], v[134:135] op_sel_hi:[1,0]
	s_nop 0
	v_pk_mul_f32 v[132:133], v[32:33], v[134:135] op_sel_hi:[1,0]
	v_pk_mul_f32 v[130:131], v[30:31], v[134:135] op_sel_hi:[1,0]
	v_pk_mul_f32 v[134:135], v[26:27], v[134:135] op_sel_hi:[1,0]
	v_cvt_pk_bf16_f32 v130, v130, v131
	v_cvt_pk_bf16_f32 v131, v132, v133
	v_cvt_pk_bf16_f32 v132, v134, v135
	v_cvt_pk_bf16_f32 v133, v138, v139
	global_store_dwordx4 v[136:137], v[130:133], off offset:256
	s_nop 1
	v_add_u32_e32 v130, s14, v206
	v_ashrrev_i32_e32 v131, 31, v130
	v_lshl_add_u64 v[132:133], v[130:131], 2, s[44:45]
	v_mov_b32_e32 v132, v218
	v_lshlrev_b64 v[136:137], 11, v[130:131]
	v_lshl_add_u64 v[136:137], s[16:17], 0, v[136:137]
	v_lshl_add_u64 v[136:137], v[136:137], 0, s[2:3]
	v_lshl_add_u64 v[136:137], v[136:137], 0, s[8:9]
	v_lshl_add_u64 v[136:137], v[136:137], 0, v[0:1]
	s_nop 0
	v_fmamk_f32 v132, v132, 0x3c000000, v202
	v_rsq_f32_e32 v134, v132
	s_nop 0
	v_pk_mul_f32 v[132:133], v[56:57], v[134:135] op_sel_hi:[1,0]
	v_pk_mul_f32 v[130:131], v[54:55], v[134:135] op_sel_hi:[1,0]
	v_pk_mul_f32 v[138:139], v[52:53], v[134:135] op_sel_hi:[1,0]
	v_pk_mul_f32 v[140:141], v[50:51], v[134:135] op_sel_hi:[1,0]
	v_cvt_pk_bf16_f32 v130, v130, v131
	v_cvt_pk_bf16_f32 v131, v132, v133
	v_cvt_pk_bf16_f32 v132, v140, v141
	v_cvt_pk_bf16_f32 v133, v138, v139
	global_store_dwordx4 v[136:137], v[130:133], off
	v_pk_mul_f32 v[138:139], v[20:21], v[134:135] op_sel_hi:[1,0]
	s_nop 0
	v_pk_mul_f32 v[132:133], v[24:25], v[134:135] op_sel_hi:[1,0]
	v_pk_mul_f32 v[130:131], v[22:23], v[134:135] op_sel_hi:[1,0]
	v_pk_mul_f32 v[134:135], v[18:19], v[134:135] op_sel_hi:[1,0]
	v_cvt_pk_bf16_f32 v130, v130, v131
	v_cvt_pk_bf16_f32 v131, v132, v133
	v_cvt_pk_bf16_f32 v132, v134, v135
	v_cvt_pk_bf16_f32 v133, v138, v139
	global_store_dwordx4 v[136:137], v[130:133], off offset:256
	s_nop 1
	v_add_u32_e32 v130, s14, v207
	v_ashrrev_i32_e32 v131, 31, v130
	v_lshl_add_u64 v[132:133], v[130:131], 2, s[44:45]
	v_mov_b32_e32 v132, v219
	v_lshlrev_b64 v[136:137], 11, v[130:131]
	v_lshl_add_u64 v[136:137], s[16:17], 0, v[136:137]
	v_lshl_add_u64 v[136:137], v[136:137], 0, s[2:3]
	v_lshl_add_u64 v[136:137], v[136:137], 0, s[8:9]
	v_lshl_add_u64 v[136:137], v[136:137], 0, v[0:1]
	s_nop 0
	v_fmamk_f32 v132, v132, 0x3c000000, v202
	v_rsq_f32_e32 v134, v132
	s_nop 0
	v_pk_mul_f32 v[132:133], v[48:49], v[134:135] op_sel_hi:[1,0]
	v_pk_mul_f32 v[130:131], v[46:47], v[134:135] op_sel_hi:[1,0]
	v_pk_mul_f32 v[138:139], v[44:45], v[134:135] op_sel_hi:[1,0]
	v_pk_mul_f32 v[140:141], v[42:43], v[134:135] op_sel_hi:[1,0]
	v_cvt_pk_bf16_f32 v130, v130, v131
	v_cvt_pk_bf16_f32 v131, v132, v133
	v_cvt_pk_bf16_f32 v132, v140, v141
	v_cvt_pk_bf16_f32 v133, v138, v139
	global_store_dwordx4 v[136:137], v[130:133], off
	v_pk_mul_f32 v[138:139], v[12:13], v[134:135] op_sel_hi:[1,0]
	s_nop 0
	v_pk_mul_f32 v[132:133], v[16:17], v[134:135] op_sel_hi:[1,0]
	v_pk_mul_f32 v[130:131], v[14:15], v[134:135] op_sel_hi:[1,0]
	v_pk_mul_f32 v[134:135], v[10:11], v[134:135] op_sel_hi:[1,0]
	v_cvt_pk_bf16_f32 v130, v130, v131
	v_cvt_pk_bf16_f32 v131, v132, v133
	v_cvt_pk_bf16_f32 v132, v134, v135
	v_cvt_pk_bf16_f32 v133, v138, v139
	global_store_dwordx4 v[136:137], v[130:133], off offset:256
	s_nop 1
	v_add_u32_e32 v130, s14, v208
	v_ashrrev_i32_e32 v131, 31, v130
	v_lshl_add_u64 v[132:133], v[130:131], 2, s[44:45]
	v_mov_b32_e32 v132, v220
	v_lshlrev_b64 v[136:137], 11, v[130:131]
	v_lshl_add_u64 v[136:137], s[16:17], 0, v[136:137]
	v_lshl_add_u64 v[136:137], v[136:137], 0, s[2:3]
	v_lshl_add_u64 v[136:137], v[136:137], 0, s[8:9]
	v_lshl_add_u64 v[136:137], v[136:137], 0, v[0:1]
	s_nop 0
	v_fmamk_f32 v132, v132, 0x3c000000, v202
	v_rsq_f32_e32 v134, v132
	s_nop 0
	v_pk_mul_f32 v[132:133], v[40:41], v[134:135] op_sel_hi:[1,0]
	v_pk_mul_f32 v[130:131], v[38:39], v[134:135] op_sel_hi:[1,0]
	v_pk_mul_f32 v[138:139], v[36:37], v[134:135] op_sel_hi:[1,0]
	v_pk_mul_f32 v[140:141], v[34:35], v[134:135] op_sel_hi:[1,0]
	v_cvt_pk_bf16_f32 v130, v130, v131
	v_cvt_pk_bf16_f32 v131, v132, v133
	v_cvt_pk_bf16_f32 v132, v140, v141
	v_cvt_pk_bf16_f32 v133, v138, v139
	global_store_dwordx4 v[136:137], v[130:133], off
	v_pk_mul_f32 v[138:139], v[4:5], v[134:135] op_sel_hi:[1,0]
	s_nop 0
	v_pk_mul_f32 v[132:133], v[8:9], v[134:135] op_sel_hi:[1,0]
	v_pk_mul_f32 v[130:131], v[6:7], v[134:135] op_sel_hi:[1,0]
	v_pk_mul_f32 v[134:135], v[2:3], v[134:135] op_sel_hi:[1,0]
	v_cvt_pk_bf16_f32 v130, v130, v131
	v_cvt_pk_bf16_f32 v131, v132, v133
	v_cvt_pk_bf16_f32 v132, v134, v135
	v_cvt_pk_bf16_f32 v133, v138, v139
	global_store_dwordx4 v[136:137], v[130:133], off offset:256

; __device__ __forceinline__ unsigned cvtpk(float lo, float hi) { f32x2 v = {lo, hi}; bf16x2_t b = __builtin_convertvector(v, bf16x2_t); return __builtin_bit_cast(unsigned, b); }
; __device__ __forceinline__ float fexp2(float x) { return __builtin_amdgcn_exp2f(x); }
; __device__ __forceinline__ u32x4 pack8(f32x4 a, f32x4 b) { u32x4 o; o.x = cvtpk(a[0], a[1]); o.y = cvtpk(a[2], a[3]); o.z = cvtpk(b[0], b[1]); o.w = cvtpk(b[2], b[3]); return o; }
;     template <int KIND> __device__ __forceinline__ void run(f32x4 (&acc)[2][2][4][2], const GUnit& u, int wr, int wc, int fr, int fq, int tid) const {
;     ...
;                 } else if (kind == EP_Q) {
;                     const float rs = __builtin_amdgcn_rsqf(ssq_q[row] * (1.f / 256.f) + EPS) * QSCALE;
;                     const int tok = row % TOK;
; #pragma unroll
;                     for (int bj = 0; bj < 2; ++bj) {
;                         const int head = 2 * pn + bj;
;                         f32x4 v0 = acc[ai][bj][m][0] * rs, v1 = acc[ai][bj][m][1] * rs;
;                         if (wc < 2) { *(u32x4*)(Qb + (size_t)row * 768 + head * 96 + wc * 32 + 8 * fq) = pack8(v0, v1); }
;                         else { f32x4 o = v0; const int g = 4 * (wc - 2) + fq;
;                             if (tok >= CTXL) { const int t = tok - CTXL; const int pos = (wc == 2) ? (t >> 6) : (t & 63);
; #pragma unroll
;                                 for (int j = 0; j < 4; ++j) { const float rv = (float)pos * (fexp2(-(float)(4 * (fq & 1) + j) * (13.287712379549449f / 8.f)) * 0.15915494309189535f);     const float fr_ = rv - floorf(rv); o[j] = v0[j] * __builtin_amdgcn_cosf(fr_) + v1[j] * __builtin_amdgcn_sinf(fr_); } }
;                             u32x2 pk; pk.x = cvtpk(o[0], o[1]); pk.y = cvtpk(o[2], o[3]);
;                             *(u32x2*)(Qb + (size_t)row * 768 + head * 96 + 64 + 4 * g) = pk; }
;                     }
.LBB0_460:
	s_and_b64 vcc, exec, s[2:3]
	s_cbranch_vccz .LBB0_561
	s_cmp_gt_i32 s29, 0
	s_mov_b64 s[2:3], -1
	s_cbranch_scc0 .LBB0_559
	v_mov_b32_e32 v0, v189
	s_lshl_b32 s50, s42, 8
	v_add_u32_e32 v132, s50, v196
	v_readlane_b32 s0, v252, 13
	v_ashrrev_i32_e32 v133, 31, v132
	v_readlane_b32 s1, v252, 14
	v_readlane_b32 s2, v255, 42
	v_readlane_b32 s3, v255, 43
	v_lshl_add_u64 v[130:131], v[132:133], 2, s[0:1]
	global_load_dword v0, v[130:131], off
	v_add_u32_e32 v222, s50, v198
	v_ashrrev_i32_e32 v223, 31, v222
	v_lshl_add_u64 v[222:223], v[222:223], 2, s[0:1]
	global_load_dword v214, v[222:223], off
	v_add_u32_e32 v222, s50, v199
	v_ashrrev_i32_e32 v223, 31, v222
	v_lshl_add_u64 v[222:223], v[222:223], 2, s[0:1]
	global_load_dword v215, v[222:223], off
	v_add_u32_e32 v222, s50, v200
	v_ashrrev_i32_e32 v223, 31, v222
	v_lshl_add_u64 v[222:223], v[222:223], 2, s[0:1]
	global_load_dword v216, v[222:223], off
	v_add_u32_e32 v222, s50, v201
	v_ashrrev_i32_e32 v223, 31, v222
	v_lshl_add_u64 v[222:223], v[222:223], 2, s[0:1]
	global_load_dword v217, v[222:223], off
	v_add_u32_e32 v222, s50, v206
	v_ashrrev_i32_e32 v223, 31, v222
	v_lshl_add_u64 v[222:223], v[222:223], 2, s[0:1]
	global_load_dword v218, v[222:223], off
	v_add_u32_e32 v222, s50, v207
	v_ashrrev_i32_e32 v223, 31, v222
	v_lshl_add_u64 v[222:223], v[222:223], 2, s[0:1]
	global_load_dword v219, v[222:223], off
	v_add_u32_e32 v222, s50, v208
	v_ashrrev_i32_e32 v223, 31, v222
	v_lshl_add_u64 v[222:223], v[222:223], 2, s[0:1]
	global_load_dword v220, v[222:223], off
	s_mov_b32 s0, 0x38e38e39
	s_and_b64 vcc, exec, s[2:3]
	s_mul_i32 s2, s28, 0xc0
	s_waitcnt vmcnt(0)
	v_fmamk_f32 v0, v0, 0x3b800000, v202
	v_rsq_f32_e32 v0, v0
	s_nop 0
	v_mul_f32_e32 v130, 0x3e16c740, v0
	v_mul_hi_i32 v0, v132, s0
	v_lshrrev_b32_e32 v131, 31, v0
	v_ashrrev_i32_e32 v0, 9, v0
	v_add_u32_e32 v0, v0, v131
	v_mul_i32_i24_e32 v0, 0x900, v0
	v_sub_u32_e32 v0, v132, v0
	s_movk_i32 s0, 0xff
	v_add_u32_e32 v131, 0xffffff00, v0
	v_cmp_lt_i32_e64 s[44:45], s0, v0
	v_lshrrev_b32_e32 v131, 6, v131
	v_and_b32_e32 v0, 15, v0
	v_cndmask_b32_e64 v0, v0, v131, s[94:95]
	v_cvt_f32_u32_e32 v146, v0
	s_movk_i32 s0, 0x600
	v_mad_i64_i32 v[140:141], s[0:1], v132, s0, 0
	v_pk_mul_f32 v[132:133], v[128:129], v[130:131] op_sel_hi:[1,0]
	v_pk_mul_f32 v[138:139], v[126:127], v[130:131] op_sel_hi:[1,0]
	v_pk_mul_f32 v[134:135], v[124:125], v[130:131] op_sel_hi:[1,0]
	v_pk_mul_f32 v[136:137], v[122:123], v[130:131] op_sel_hi:[1,0]
	s_mov_b64 s[0:1], -1
	s_cbranch_vccz .LBB0_466
	v_mov_b32_e32 v142, v138
	v_mov_b32_e32 v143, v139
	v_mov_b32_e32 v144, v132
	v_mov_b32_e32 v145, v133
	s_and_saveexec_b64 s[0:1], s[44:45]
	s_cbranch_execz .LBB0_465
	v_mul_f32_e32 v131, v210, v146
	v_floor_f32_e32 v131, v131
	v_fma_f32 v131, v210, v146, -v131
	v_sin_f32_e32 v143, v131
	v_cos_f32_e32 v145, v131
	v_mul_f32_e32 v131, v212, v146
	v_mul_f32_e32 v0, v209, v146
	v_mul_f32_e32 v144, v211, v146
	v_floor_f32_e32 v131, v131
	v_floor_f32_e32 v0, v0
	v_floor_f32_e32 v144, v144
	v_fma_f32 v131, v212, v146, -v131
	v_fma_f32 v0, v209, v146, -v0
	v_fma_f32 v147, v211, v146, -v144
	v_cos_f32_e32 v150, v131
	v_sin_f32_e32 v151, v131
	v_sin_f32_e32 v142, v0
	v_cos_f32_e32 v148, v147
	v_cos_f32_e32 v144, v0
	v_sin_f32_e32 v0, v147
	v_mov_b32_e32 v154, v133
	v_mov_b32_e32 v155, v135
	v_pk_mul_f32 v[150:151], v[150:151], v[154:155]
	v_pk_mul_f32 v[142:143], v[142:143], v[136:137]
	v_mul_f32_e32 v148, v148, v132
	v_mul_f32_e32 v152, v0, v134
	v_mov_b32_e32 v149, v150
	v_mov_b32_e32 v153, v151
	v_pk_fma_f32 v[142:143], v[144:145], v[138:139], v[142:143]
	v_pk_add_f32 v[144:145], v[148:149], v[152:153]

; __device__ __forceinline__ unsigned cvtpk(float lo, float hi) { f32x2 v = {lo, hi}; bf16x2_t b = __builtin_convertvector(v, bf16x2_t); return __builtin_bit_cast(unsigned, b); }
; __device__ __forceinline__ float fexp2(float x) { return __builtin_amdgcn_exp2f(x); }
; __device__ __forceinline__ u32x4 pack8(f32x4 a, f32x4 b) { u32x4 o; o.x = cvtpk(a[0], a[1]); o.y = cvtpk(a[2], a[3]); o.z = cvtpk(b[0], b[1]); o.w = cvtpk(b[2], b[3]); return o; }
;     template <int KIND> __device__ __forceinline__ void run(f32x4 (&acc)[2][2][4][2], const GUnit& u, int wr, int wc, int fr, int fq, int tid) const {
;     ...
;                 } else if (kind == EP_Q) {
;                     const float rs = __builtin_amdgcn_rsqf(ssq_q[row] * (1.f / 256.f) + EPS) * QSCALE;
;                     const int tok = row % TOK;
; #pragma unroll
;                     for (int bj = 0; bj < 2; ++bj) {
;                         const int head = 2 * pn + bj;
;                         f32x4 v0 = acc[ai][bj][m][0] * rs, v1 = acc[ai][bj][m][1] * rs;
;                         if (wc < 2) { *(u32x4*)(Qb + (size_t)row * 768 + head * 96 + wc * 32 + 8 * fq) = pack8(v0, v1); }
;                         else { f32x4 o = v0; const int g = 4 * (wc - 2) + fq;
;                             if (tok >= CTXL) { const int t = tok - CTXL; const int pos = (wc == 2) ? (t >> 6) : (t & 63);
; #pragma unroll
;                                 for (int j = 0; j < 4; ++j) { const float rv = (float)pos * (fexp2(-(float)(4 * (fq & 1) + j) * (13.287712379549449f / 8.f)) * 0.15915494309189535f);     const float fr_ = rv - floorf(rv); o[j] = v0[j] * __builtin_amdgcn_cosf(fr_) + v1[j] * __builtin_amdgcn_sinf(fr_); } }
;                             u32x2 pk; pk.x = cvtpk(o[0], o[1]); pk.y = cvtpk(o[2], o[3]);
;                             *(u32x2*)(Qb + (size_t)row * 768 + head * 96 + 64 + 4 * g) = pk; }
;                     }
.LBB0_474:
	v_add_u32_e32 v132, s50, v198
	v_readlane_b32 s16, v252, 13
	v_ashrrev_i32_e32 v133, 31, v132
	v_readlane_b32 s17, v252, 14
	s_mov_b32 s3, 0x38e38e39
	s_and_b64 vcc, exec, s[0:1]
	v_lshl_add_u64 v[130:131], v[132:133], 2, s[16:17]
	v_mov_b32_e32 v0, v214
	v_mul_hi_i32 v133, v132, s3
	v_lshrrev_b32_e32 v134, 31, v133
	v_ashrrev_i32_e32 v133, 9, v133
	v_add_u32_e32 v133, v133, v134
	s_movk_i32 s3, 0x600
	v_mul_i32_i24_e32 v133, 0x900, v133
	v_mad_i64_i32 v[130:131], s[16:17], v132, s3, 0
	v_sub_u32_e32 v132, v132, v133
	s_movk_i32 s3, 0xff
	v_add_u32_e32 v133, 0xffffff00, v132
	v_cmp_lt_i32_e64 s[44:45], s3, v132
	v_and_b32_e32 v132, 31, v132
	v_lshrrev_b32_e32 v133, 6, v133
	v_cndmask_b32_e64 v132, v132, v133, s[94:95]
	v_cvt_f32_u32_e32 v146, v132
	s_mov_b64 s[16:17], -1
	s_nop 0
	v_fmamk_f32 v0, v0, 0x3b800000, v202
	v_rsq_f32_e32 v0, v0
	s_nop 0
	v_mul_f32_e32 v132, 0x3e16c740, v0
	v_pk_mul_f32 v[134:135], v[120:121], v[132:133] op_sel_hi:[1,0]
	v_pk_mul_f32 v[140:141], v[118:119], v[132:133] op_sel_hi:[1,0]
	v_pk_mul_f32 v[136:137], v[116:117], v[132:133] op_sel_hi:[1,0]
	v_pk_mul_f32 v[138:139], v[114:115], v[132:133] op_sel_hi:[1,0]
	s_cbranch_vccnz .LBB0_478
	v_mov_b32_e32 v142, v140
	v_mov_b32_e32 v143, v141
	v_mov_b32_e32 v144, v134
	v_mov_b32_e32 v145, v135
	s_and_saveexec_b64 s[16:17], s[44:45]
	s_cbranch_execz .LBB0_477
	v_mul_f32_e32 v133, v210, v146
	v_floor_f32_e32 v133, v133
	v_fma_f32 v133, v210, v146, -v133
	v_sin_f32_e32 v143, v133
	v_cos_f32_e32 v145, v133
	v_mul_f32_e32 v133, v212, v146
	v_mul_f32_e32 v0, v209, v146
	v_mul_f32_e32 v144, v211, v146
	v_floor_f32_e32 v133, v133
	v_floor_f32_e32 v0, v0
	v_floor_f32_e32 v144, v144
	v_fma_f32 v133, v212, v146, -v133
	v_fma_f32 v0, v209, v146, -v0
	v_fma_f32 v147, v211, v146, -v144
	v_cos_f32_e32 v150, v133
	v_sin_f32_e32 v151, v133
	v_sin_f32_e32 v142, v0
	v_cos_f32_e32 v148, v147
	v_cos_f32_e32 v144, v0
	v_sin_f32_e32 v0, v147
	v_mov_b32_e32 v154, v135
	v_mov_b32_e32 v155, v137
	v_pk_mul_f32 v[150:151], v[150:151], v[154:155]
	v_pk_mul_f32 v[142:143], v[142:143], v[138:139]
	v_mul_f32_e32 v148, v148, v134
	v_mul_f32_e32 v152, v0, v136
	v_mov_b32_e32 v149, v150
	v_mov_b32_e32 v153, v151
	v_pk_fma_f32 v[142:143], v[144:145], v[140:141], v[142:143]
	v_pk_add_f32 v[144:145], v[148:149], v[152:153]

; __device__ __forceinline__ unsigned cvtpk(float lo, float hi) { f32x2 v = {lo, hi}; bf16x2_t b = __builtin_convertvector(v, bf16x2_t); return __builtin_bit_cast(unsigned, b); }
; __device__ __forceinline__ float fexp2(float x) { return __builtin_amdgcn_exp2f(x); }
; __device__ __forceinline__ u32x4 pack8(f32x4 a, f32x4 b) { u32x4 o; o.x = cvtpk(a[0], a[1]); o.y = cvtpk(a[2], a[3]); o.z = cvtpk(b[0], b[1]); o.w = cvtpk(b[2], b[3]); return o; }
;     template <int KIND> __device__ __forceinline__ void run(f32x4 (&acc)[2][2][4][2], const GUnit& u, int wr, int wc, int fr, int fq, int tid) const {
;     ...
;                 } else if (kind == EP_Q) {
;                     const float rs = __builtin_amdgcn_rsqf(ssq_q[row] * (1.f / 256.f) + EPS) * QSCALE;
;                     const int tok = row % TOK;
; #pragma unroll
;                     for (int bj = 0; bj < 2; ++bj) {
;                         const int head = 2 * pn + bj;
;                         f32x4 v0 = acc[ai][bj][m][0] * rs, v1 = acc[ai][bj][m][1] * rs;
;                         if (wc < 2) { *(u32x4*)(Qb + (size_t)row * 768 + head * 96 + wc * 32 + 8 * fq) = pack8(v0, v1); }
;                         else { f32x4 o = v0; const int g = 4 * (wc - 2) + fq;
;                             if (tok >= CTXL) { const int t = tok - CTXL; const int pos = (wc == 2) ? (t >> 6) : (t & 63);
; #pragma unroll
;                                 for (int j = 0; j < 4; ++j) { const float rv = (float)pos * (fexp2(-(float)(4 * (fq & 1) + j) * (13.287712379549449f / 8.f)) * 0.15915494309189535f);     const float fr_ = rv - floorf(rv); o[j] = v0[j] * __builtin_amdgcn_cosf(fr_) + v1[j] * __builtin_amdgcn_sinf(fr_); } }
;                             u32x2 pk; pk.x = cvtpk(o[0], o[1]); pk.y = cvtpk(o[2], o[3]);
;                             *(u32x2*)(Qb + (size_t)row * 768 + head * 96 + 64 + 4 * g) = pk; }
;                     }
.LBB0_486:
	v_add_u32_e32 v132, s50, v199
	v_readlane_b32 s16, v252, 13
	v_ashrrev_i32_e32 v133, 31, v132
	v_readlane_b32 s17, v252, 14
	s_mov_b32 s3, 0x38e38e39
	s_and_b64 vcc, exec, s[0:1]
	v_lshl_add_u64 v[130:131], v[132:133], 2, s[16:17]
	v_mov_b32_e32 v0, v215
	v_mul_hi_i32 v133, v132, s3
	v_lshrrev_b32_e32 v134, 31, v133
	v_ashrrev_i32_e32 v133, 9, v133
	v_add_u32_e32 v133, v133, v134
	s_movk_i32 s3, 0x600
	v_mul_i32_i24_e32 v133, 0x900, v133
	v_mad_i64_i32 v[130:131], s[16:17], v132, s3, 0
	v_sub_u32_e32 v132, v132, v133
	s_movk_i32 s3, 0xff
	v_add_u32_e32 v133, 0xffffff00, v132
	v_cmp_lt_i32_e64 s[44:45], s3, v132
	v_and_b32_e32 v132, 47, v132
	v_lshrrev_b32_e32 v133, 6, v133
	v_cndmask_b32_e64 v132, v132, v133, s[94:95]
	v_cvt_f32_u32_e32 v146, v132
	s_mov_b64 s[16:17], -1
	s_nop 0
	v_fmamk_f32 v0, v0, 0x3b800000, v202
	v_rsq_f32_e32 v0, v0
	s_nop 0
	v_mul_f32_e32 v132, 0x3e16c740, v0
	v_pk_mul_f32 v[134:135], v[112:113], v[132:133] op_sel_hi:[1,0]
	v_pk_mul_f32 v[140:141], v[110:111], v[132:133] op_sel_hi:[1,0]
	v_pk_mul_f32 v[136:137], v[108:109], v[132:133] op_sel_hi:[1,0]
	v_pk_mul_f32 v[138:139], v[106:107], v[132:133] op_sel_hi:[1,0]
	s_cbranch_vccnz .LBB0_490
	v_mov_b32_e32 v142, v140
	v_mov_b32_e32 v143, v141
	v_mov_b32_e32 v144, v134
	v_mov_b32_e32 v145, v135
	s_and_saveexec_b64 s[16:17], s[44:45]
	s_cbranch_execz .LBB0_489
	v_mul_f32_e32 v133, v210, v146
	v_floor_f32_e32 v133, v133
	v_fma_f32 v133, v210, v146, -v133
	v_sin_f32_e32 v143, v133
	v_cos_f32_e32 v145, v133
	v_mul_f32_e32 v133, v212, v146
	v_mul_f32_e32 v0, v209, v146
	v_mul_f32_e32 v144, v211, v146
	v_floor_f32_e32 v133, v133
	v_floor_f32_e32 v0, v0
	v_floor_f32_e32 v144, v144
	v_fma_f32 v133, v212, v146, -v133
	v_fma_f32 v0, v209, v146, -v0
	v_fma_f32 v147, v211, v146, -v144
	v_cos_f32_e32 v150, v133
	v_sin_f32_e32 v151, v133
	v_sin_f32_e32 v142, v0
	v_cos_f32_e32 v148, v147
	v_cos_f32_e32 v144, v0
	v_sin_f32_e32 v0, v147
	v_mov_b32_e32 v154, v135
	v_mov_b32_e32 v155, v137
	v_pk_mul_f32 v[150:151], v[150:151], v[154:155]
	v_pk_mul_f32 v[142:143], v[142:143], v[138:139]
	v_mul_f32_e32 v148, v148, v134
	v_mul_f32_e32 v152, v0, v136
	v_mov_b32_e32 v149, v150
	v_mov_b32_e32 v153, v151
	v_pk_fma_f32 v[142:143], v[144:145], v[140:141], v[142:143]
	v_pk_add_f32 v[144:145], v[148:149], v[152:153]

; __device__ __forceinline__ unsigned cvtpk(float lo, float hi) { f32x2 v = {lo, hi}; bf16x2_t b = __builtin_convertvector(v, bf16x2_t); return __builtin_bit_cast(unsigned, b); }
; __device__ __forceinline__ float fexp2(float x) { return __builtin_amdgcn_exp2f(x); }
; __device__ __forceinline__ u32x4 pack8(f32x4 a, f32x4 b) { u32x4 o; o.x = cvtpk(a[0], a[1]); o.y = cvtpk(a[2], a[3]); o.z = cvtpk(b[0], b[1]); o.w = cvtpk(b[2], b[3]); return o; }
;     template <int KIND> __device__ __forceinline__ void run(f32x4 (&acc)[2][2][4][2], const GUnit& u, int wr, int wc, int fr, int fq, int tid) const {
;     ...
;                 } else if (kind == EP_Q) {
;                     const float rs = __builtin_amdgcn_rsqf(ssq_q[row] * (1.f / 256.f) + EPS) * QSCALE;
;                     const int tok = row % TOK;
; #pragma unroll
;                     for (int bj = 0; bj < 2; ++bj) {
;                         const int head = 2 * pn + bj;
;                         f32x4 v0 = acc[ai][bj][m][0] * rs, v1 = acc[ai][bj][m][1] * rs;
;                         if (wc < 2) { *(u32x4*)(Qb + (size_t)row * 768 + head * 96 + wc * 32 + 8 * fq) = pack8(v0, v1); }
;                         else { f32x4 o = v0; const int g = 4 * (wc - 2) + fq;
;                             if (tok >= CTXL) { const int t = tok - CTXL; const int pos = (wc == 2) ? (t >> 6) : (t & 63);
; #pragma unroll
;                                 for (int j = 0; j < 4; ++j) { const float rv = (float)pos * (fexp2(-(float)(4 * (fq & 1) + j) * (13.287712379549449f / 8.f)) * 0.15915494309189535f);     const float fr_ = rv - floorf(rv); o[j] = v0[j] * __builtin_amdgcn_cosf(fr_) + v1[j] * __builtin_amdgcn_sinf(fr_); } }
;                             u32x2 pk; pk.x = cvtpk(o[0], o[1]); pk.y = cvtpk(o[2], o[3]);
;                             *(u32x2*)(Qb + (size_t)row * 768 + head * 96 + 64 + 4 * g) = pk; }
;                     }
.LBB0_498:
	v_add_u32_e32 v132, s50, v200
	v_readlane_b32 s16, v252, 13
	v_ashrrev_i32_e32 v133, 31, v132
	v_readlane_b32 s17, v252, 14
	s_mov_b32 s3, 0x38e38e39
	s_and_b64 vcc, exec, s[0:1]
	v_lshl_add_u64 v[130:131], v[132:133], 2, s[16:17]
	v_mov_b32_e32 v0, v216
	v_mul_hi_i32 v133, v132, s3
	v_lshrrev_b32_e32 v134, 31, v133
	v_ashrrev_i32_e32 v133, 9, v133
	v_add_u32_e32 v133, v133, v134
	s_movk_i32 s3, 0x600
	v_mul_i32_i24_e32 v133, 0x900, v133
	v_mad_i64_i32 v[130:131], s[16:17], v132, s3, 0
	v_sub_u32_e32 v132, v132, v133
	s_movk_i32 s3, 0xff
	v_add_u32_e32 v133, 0xffffff00, v132
	v_cmp_lt_i32_e64 s[44:45], s3, v132
	v_and_b32_e32 v132, 63, v132
	v_lshrrev_b32_e32 v133, 6, v133
	v_cndmask_b32_e64 v132, v132, v133, s[94:95]
	v_cvt_f32_u32_e32 v146, v132
	s_mov_b64 s[16:17], -1
	s_nop 0
	v_fmamk_f32 v0, v0, 0x3b800000, v202
	v_rsq_f32_e32 v0, v0
	s_nop 0
	v_mul_f32_e32 v132, 0x3e16c740, v0
	v_pk_mul_f32 v[134:135], v[104:105], v[132:133] op_sel_hi:[1,0]
	v_pk_mul_f32 v[140:141], v[102:103], v[132:133] op_sel_hi:[1,0]
	v_pk_mul_f32 v[136:137], v[100:101], v[132:133] op_sel_hi:[1,0]
	v_pk_mul_f32 v[138:139], v[98:99], v[132:133] op_sel_hi:[1,0]
	s_cbranch_vccnz .LBB0_502
	v_mov_b32_e32 v142, v140
	v_mov_b32_e32 v143, v141
	v_mov_b32_e32 v144, v134
	v_mov_b32_e32 v145, v135
	s_and_saveexec_b64 s[16:17], s[44:45]
	s_cbranch_execz .LBB0_501
	v_mul_f32_e32 v133, v210, v146
	v_floor_f32_e32 v133, v133
	v_fma_f32 v133, v210, v146, -v133
	v_sin_f32_e32 v143, v133
	v_cos_f32_e32 v145, v133
	v_mul_f32_e32 v133, v212, v146
	v_mul_f32_e32 v0, v209, v146
	v_mul_f32_e32 v144, v211, v146
	v_floor_f32_e32 v133, v133
	v_floor_f32_e32 v0, v0
	v_floor_f32_e32 v144, v144
	v_fma_f32 v133, v212, v146, -v133
	v_fma_f32 v0, v209, v146, -v0
	v_fma_f32 v147, v211, v146, -v144
	v_cos_f32_e32 v150, v133
	v_sin_f32_e32 v151, v133
	v_sin_f32_e32 v142, v0
	v_cos_f32_e32 v148, v147
	v_cos_f32_e32 v144, v0
	v_sin_f32_e32 v0, v147
	v_mov_b32_e32 v154, v135
	v_mov_b32_e32 v155, v137
	v_pk_mul_f32 v[150:151], v[150:151], v[154:155]
	v_pk_mul_f32 v[142:143], v[142:143], v[138:139]
	v_mul_f32_e32 v148, v148, v134
	v_mul_f32_e32 v152, v0, v136
	v_mov_b32_e32 v149, v150
	v_mov_b32_e32 v153, v151
	v_pk_fma_f32 v[142:143], v[144:145], v[140:141], v[142:143]
	v_pk_add_f32 v[144:145], v[148:149], v[152:153]

; __device__ __forceinline__ unsigned cvtpk(float lo, float hi) { f32x2 v = {lo, hi}; bf16x2_t b = __builtin_convertvector(v, bf16x2_t); return __builtin_bit_cast(unsigned, b); }
; __device__ __forceinline__ float fexp2(float x) { return __builtin_amdgcn_exp2f(x); }
; __device__ __forceinline__ u32x4 pack8(f32x4 a, f32x4 b) { u32x4 o; o.x = cvtpk(a[0], a[1]); o.y = cvtpk(a[2], a[3]); o.z = cvtpk(b[0], b[1]); o.w = cvtpk(b[2], b[3]); return o; }
;     template <int KIND> __device__ __forceinline__ void run(f32x4 (&acc)[2][2][4][2], const GUnit& u, int wr, int wc, int fr, int fq, int tid) const {
;     ...
;                 } else if (kind == EP_Q) {
;                     const float rs = __builtin_amdgcn_rsqf(ssq_q[row] * (1.f / 256.f) + EPS) * QSCALE;
;                     const int tok = row % TOK;
; #pragma unroll
;                     for (int bj = 0; bj < 2; ++bj) {
;                         const int head = 2 * pn + bj;
;                         f32x4 v0 = acc[ai][bj][m][0] * rs, v1 = acc[ai][bj][m][1] * rs;
;                         if (wc < 2) { *(u32x4*)(Qb + (size_t)row * 768 + head * 96 + wc * 32 + 8 * fq) = pack8(v0, v1); }
;                         else { f32x4 o = v0; const int g = 4 * (wc - 2) + fq;
;                             if (tok >= CTXL) { const int t = tok - CTXL; const int pos = (wc == 2) ? (t >> 6) : (t & 63);
; #pragma unroll
;                                 for (int j = 0; j < 4; ++j) { const float rv = (float)pos * (fexp2(-(float)(4 * (fq & 1) + j) * (13.287712379549449f / 8.f)) * 0.15915494309189535f);     const float fr_ = rv - floorf(rv); o[j] = v0[j] * __builtin_amdgcn_cosf(fr_) + v1[j] * __builtin_amdgcn_sinf(fr_); } }
;                             u32x2 pk; pk.x = cvtpk(o[0], o[1]); pk.y = cvtpk(o[2], o[3]);
;                             *(u32x2*)(Qb + (size_t)row * 768 + head * 96 + 64 + 4 * g) = pk; }
;                     }
.LBB0_510:
	v_add_u32_e32 v132, s50, v201
	v_readlane_b32 s16, v252, 13
	v_ashrrev_i32_e32 v133, 31, v132
	v_readlane_b32 s17, v252, 14
	s_mov_b32 s3, 0x38e38e39
	s_and_b64 vcc, exec, s[0:1]
	v_lshl_add_u64 v[130:131], v[132:133], 2, s[16:17]
	v_mov_b32_e32 v0, v217
	v_mul_hi_i32 v133, v132, s3
	v_lshrrev_b32_e32 v134, 31, v133
	v_ashrrev_i32_e32 v133, 9, v133
	v_add_u32_e32 v133, v133, v134
	s_movk_i32 s3, 0x600
	v_mul_i32_i24_e32 v133, 0x900, v133
	v_mad_i64_i32 v[130:131], s[16:17], v132, s3, 0
	v_sub_u32_e32 v132, v132, v133
	s_movk_i32 s3, 0xff
	v_add_u32_e32 v133, 0xffffff00, v132
	v_cmp_lt_i32_e64 s[44:45], s3, v132
	v_and_b32_e32 v132, 15, v132
	v_lshrrev_b32_e32 v133, 6, v133
	v_cndmask_b32_e64 v132, v132, v133, s[94:95]
	v_cvt_f32_u32_e32 v146, v132
	s_mov_b64 s[16:17], -1
	s_nop 0
	v_fmamk_f32 v0, v0, 0x3b800000, v202
	v_rsq_f32_e32 v0, v0
	s_nop 0
	v_mul_f32_e32 v132, 0x3e16c740, v0
	v_pk_mul_f32 v[134:135], v[64:65], v[132:133] op_sel_hi:[1,0]
	v_pk_mul_f32 v[140:141], v[62:63], v[132:133] op_sel_hi:[1,0]
	v_pk_mul_f32 v[136:137], v[60:61], v[132:133] op_sel_hi:[1,0]
	v_pk_mul_f32 v[138:139], v[58:59], v[132:133] op_sel_hi:[1,0]
	s_cbranch_vccnz .LBB0_514
	v_mov_b32_e32 v142, v140
	v_mov_b32_e32 v143, v141
	v_mov_b32_e32 v144, v134
	v_mov_b32_e32 v145, v135
	s_and_saveexec_b64 s[16:17], s[44:45]
	s_cbranch_execz .LBB0_513
	v_mul_f32_e32 v133, v210, v146
	v_floor_f32_e32 v133, v133
	v_fma_f32 v133, v210, v146, -v133
	v_sin_f32_e32 v143, v133
	v_cos_f32_e32 v145, v133
	v_mul_f32_e32 v133, v212, v146
	v_mul_f32_e32 v0, v209, v146
	v_mul_f32_e32 v144, v211, v146
	v_floor_f32_e32 v133, v133
	v_floor_f32_e32 v0, v0
	v_floor_f32_e32 v144, v144
	v_fma_f32 v133, v212, v146, -v133
	v_fma_f32 v0, v209, v146, -v0
	v_fma_f32 v147, v211, v146, -v144
	v_cos_f32_e32 v150, v133
	v_sin_f32_e32 v151, v133
	v_sin_f32_e32 v142, v0
	v_cos_f32_e32 v148, v147
	v_cos_f32_e32 v144, v0
	v_sin_f32_e32 v0, v147
	v_mov_b32_e32 v154, v135
	v_mov_b32_e32 v155, v137
	v_pk_mul_f32 v[150:151], v[150:151], v[154:155]
	v_pk_mul_f32 v[142:143], v[142:143], v[138:139]
	v_mul_f32_e32 v148, v148, v134
	v_mul_f32_e32 v152, v0, v136
	v_mov_b32_e32 v149, v150
	v_mov_b32_e32 v153, v151
	v_pk_fma_f32 v[142:143], v[144:145], v[140:141], v[142:143]
	v_pk_add_f32 v[144:145], v[148:149], v[152:153]

; __device__ __forceinline__ unsigned cvtpk(float lo, float hi) { f32x2 v = {lo, hi}; bf16x2_t b = __builtin_convertvector(v, bf16x2_t); return __builtin_bit_cast(unsigned, b); }
; __device__ __forceinline__ float fexp2(float x) { return __builtin_amdgcn_exp2f(x); }
; __device__ __forceinline__ u32x4 pack8(f32x4 a, f32x4 b) { u32x4 o; o.x = cvtpk(a[0], a[1]); o.y = cvtpk(a[2], a[3]); o.z = cvtpk(b[0], b[1]); o.w = cvtpk(b[2], b[3]); return o; }
;     template <int KIND> __device__ __forceinline__ void run(f32x4 (&acc)[2][2][4][2], const GUnit& u, int wr, int wc, int fr, int fq, int tid) const {
;     ...
;                 } else if (kind == EP_Q) {
;                     const float rs = __builtin_amdgcn_rsqf(ssq_q[row] * (1.f / 256.f) + EPS) * QSCALE;
;                     const int tok = row % TOK;
; #pragma unroll
;                     for (int bj = 0; bj < 2; ++bj) {
;                         const int head = 2 * pn + bj;
;                         f32x4 v0 = acc[ai][bj][m][0] * rs, v1 = acc[ai][bj][m][1] * rs;
;                         if (wc < 2) { *(u32x4*)(Qb + (size_t)row * 768 + head * 96 + wc * 32 + 8 * fq) = pack8(v0, v1); }
;                         else { f32x4 o = v0; const int g = 4 * (wc - 2) + fq;
;                             if (tok >= CTXL) { const int t = tok - CTXL; const int pos = (wc == 2) ? (t >> 6) : (t & 63);
; #pragma unroll
;                                 for (int j = 0; j < 4; ++j) { const float rv = (float)pos * (fexp2(-(float)(4 * (fq & 1) + j) * (13.287712379549449f / 8.f)) * 0.15915494309189535f);     const float fr_ = rv - floorf(rv); o[j] = v0[j] * __builtin_amdgcn_cosf(fr_) + v1[j] * __builtin_amdgcn_sinf(fr_); } }
;                             u32x2 pk; pk.x = cvtpk(o[0], o[1]); pk.y = cvtpk(o[2], o[3]);
;                             *(u32x2*)(Qb + (size_t)row * 768 + head * 96 + 64 + 4 * g) = pk; }
;                     }
.LBB0_522:
	v_add_u32_e32 v132, s50, v206
	v_readlane_b32 s16, v252, 13
	v_ashrrev_i32_e32 v133, 31, v132
	v_readlane_b32 s17, v252, 14
	s_mov_b32 s3, 0x38e38e39
	s_and_b64 vcc, exec, s[0:1]
	v_lshl_add_u64 v[130:131], v[132:133], 2, s[16:17]
	v_mov_b32_e32 v0, v218
	v_mul_hi_i32 v133, v132, s3
	v_lshrrev_b32_e32 v134, 31, v133
	v_ashrrev_i32_e32 v133, 9, v133
	v_add_u32_e32 v133, v133, v134
	s_movk_i32 s3, 0x600
	v_mul_i32_i24_e32 v133, 0x900, v133
	v_mad_i64_i32 v[130:131], s[16:17], v132, s3, 0
	v_sub_u32_e32 v132, v132, v133
	s_movk_i32 s3, 0xff
	v_add_u32_e32 v133, 0xffffff00, v132
	v_cmp_lt_i32_e64 s[44:45], s3, v132
	v_and_b32_e32 v132, 31, v132
	v_lshrrev_b32_e32 v133, 6, v133
	v_cndmask_b32_e64 v132, v132, v133, s[94:95]
	v_cvt_f32_u32_e32 v146, v132
	s_mov_b64 s[16:17], -1
	s_nop 0
	v_fmamk_f32 v0, v0, 0x3b800000, v202
	v_rsq_f32_e32 v0, v0
	s_nop 0
	v_mul_f32_e32 v132, 0x3e16c740, v0
	v_pk_mul_f32 v[134:135], v[56:57], v[132:133] op_sel_hi:[1,0]
	v_pk_mul_f32 v[140:141], v[54:55], v[132:133] op_sel_hi:[1,0]
	v_pk_mul_f32 v[136:137], v[52:53], v[132:133] op_sel_hi:[1,0]
	v_pk_mul_f32 v[138:139], v[50:51], v[132:133] op_sel_hi:[1,0]
	s_cbranch_vccnz .LBB0_526
	v_mov_b32_e32 v142, v140
	v_mov_b32_e32 v143, v141
	v_mov_b32_e32 v144, v134
	v_mov_b32_e32 v145, v135
	s_and_saveexec_b64 s[16:17], s[44:45]
	s_cbranch_execz .LBB0_525
	v_mul_f32_e32 v133, v210, v146
	v_floor_f32_e32 v133, v133
	v_fma_f32 v133, v210, v146, -v133
	v_sin_f32_e32 v143, v133
	v_cos_f32_e32 v145, v133
	v_mul_f32_e32 v133, v212, v146
	v_mul_f32_e32 v0, v209, v146
	v_mul_f32_e32 v144, v211, v146
	v_floor_f32_e32 v133, v133
	v_floor_f32_e32 v0, v0
	v_floor_f32_e32 v144, v144
	v_fma_f32 v133, v212, v146, -v133
	v_fma_f32 v0, v209, v146, -v0
	v_fma_f32 v147, v211, v146, -v144
	v_cos_f32_e32 v150, v133
	v_sin_f32_e32 v151, v133
	v_sin_f32_e32 v142, v0
	v_cos_f32_e32 v148, v147
	v_cos_f32_e32 v144, v0
	v_sin_f32_e32 v0, v147
	v_mov_b32_e32 v154, v135
	v_mov_b32_e32 v155, v137
	v_pk_mul_f32 v[150:151], v[150:151], v[154:155]
	v_pk_mul_f32 v[142:143], v[142:143], v[138:139]
	v_mul_f32_e32 v148, v148, v134
	v_mul_f32_e32 v152, v0, v136
	v_mov_b32_e32 v149, v150
	v_mov_b32_e32 v153, v151
	v_pk_fma_f32 v[142:143], v[144:145], v[140:141], v[142:143]
	v_pk_add_f32 v[144:145], v[148:149], v[152:153]

; __device__ __forceinline__ unsigned cvtpk(float lo, float hi) { f32x2 v = {lo, hi}; bf16x2_t b = __builtin_convertvector(v, bf16x2_t); return __builtin_bit_cast(unsigned, b); }
; __device__ __forceinline__ float fexp2(float x) { return __builtin_amdgcn_exp2f(x); }
; __device__ __forceinline__ u32x4 pack8(f32x4 a, f32x4 b) { u32x4 o; o.x = cvtpk(a[0], a[1]); o.y = cvtpk(a[2], a[3]); o.z = cvtpk(b[0], b[1]); o.w = cvtpk(b[2], b[3]); return o; }
;     template <int KIND> __device__ __forceinline__ void run(f32x4 (&acc)[2][2][4][2], const GUnit& u, int wr, int wc, int fr, int fq, int tid) const {
;     ...
;                 } else if (kind == EP_Q) {
;                     const float rs = __builtin_amdgcn_rsqf(ssq_q[row] * (1.f / 256.f) + EPS) * QSCALE;
;                     const int tok = row % TOK;
; #pragma unroll
;                     for (int bj = 0; bj < 2; ++bj) {
;                         const int head = 2 * pn + bj;
;                         f32x4 v0 = acc[ai][bj][m][0] * rs, v1 = acc[ai][bj][m][1] * rs;
;                         if (wc < 2) { *(u32x4*)(Qb + (size_t)row * 768 + head * 96 + wc * 32 + 8 * fq) = pack8(v0, v1); }
;                         else { f32x4 o = v0; const int g = 4 * (wc - 2) + fq;
;                             if (tok >= CTXL) { const int t = tok - CTXL; const int pos = (wc == 2) ? (t >> 6) : (t & 63);
; #pragma unroll
;                                 for (int j = 0; j < 4; ++j) { const float rv = (float)pos * (fexp2(-(float)(4 * (fq & 1) + j) * (13.287712379549449f / 8.f)) * 0.15915494309189535f);     const float fr_ = rv - floorf(rv); o[j] = v0[j] * __builtin_amdgcn_cosf(fr_) + v1[j] * __builtin_amdgcn_sinf(fr_); } }
;                             u32x2 pk; pk.x = cvtpk(o[0], o[1]); pk.y = cvtpk(o[2], o[3]);
;                             *(u32x2*)(Qb + (size_t)row * 768 + head * 96 + 64 + 4 * g) = pk; }
;                     }
.LBB0_534:
	v_add_u32_e32 v132, s50, v207
	v_readlane_b32 s16, v252, 13
	v_ashrrev_i32_e32 v133, 31, v132
	v_readlane_b32 s17, v252, 14
	s_mov_b32 s3, 0x38e38e39
	s_and_b64 vcc, exec, s[0:1]
	v_lshl_add_u64 v[130:131], v[132:133], 2, s[16:17]
	v_mov_b32_e32 v0, v219
	v_mul_hi_i32 v133, v132, s3
	v_lshrrev_b32_e32 v134, 31, v133
	v_ashrrev_i32_e32 v133, 9, v133
	v_add_u32_e32 v133, v133, v134
	s_movk_i32 s3, 0x600
	v_mul_i32_i24_e32 v133, 0x900, v133
	v_mad_i64_i32 v[130:131], s[16:17], v132, s3, 0
	v_sub_u32_e32 v132, v132, v133
	s_movk_i32 s3, 0xff
	v_add_u32_e32 v133, 0xffffff00, v132
	v_cmp_lt_i32_e64 s[44:45], s3, v132
	v_and_b32_e32 v132, 47, v132
	v_lshrrev_b32_e32 v133, 6, v133
	v_cndmask_b32_e64 v132, v132, v133, s[94:95]
	v_cvt_f32_u32_e32 v146, v132
	s_mov_b64 s[16:17], -1
	s_nop 0
	v_fmamk_f32 v0, v0, 0x3b800000, v202
	v_rsq_f32_e32 v0, v0
	s_nop 0
	v_mul_f32_e32 v132, 0x3e16c740, v0
	v_pk_mul_f32 v[134:135], v[48:49], v[132:133] op_sel_hi:[1,0]
	v_pk_mul_f32 v[140:141], v[46:47], v[132:133] op_sel_hi:[1,0]
	v_pk_mul_f32 v[136:137], v[44:45], v[132:133] op_sel_hi:[1,0]
	v_pk_mul_f32 v[138:139], v[42:43], v[132:133] op_sel_hi:[1,0]
	s_cbranch_vccnz .LBB0_538
	v_mov_b32_e32 v142, v140
	v_mov_b32_e32 v143, v141
	v_mov_b32_e32 v144, v134
	v_mov_b32_e32 v145, v135
	s_and_saveexec_b64 s[16:17], s[44:45]
	s_cbranch_execz .LBB0_537
	v_mul_f32_e32 v133, v210, v146
	v_floor_f32_e32 v133, v133
	v_fma_f32 v133, v210, v146, -v133
	v_sin_f32_e32 v143, v133
	v_cos_f32_e32 v145, v133
	v_mul_f32_e32 v133, v212, v146
	v_mul_f32_e32 v0, v209, v146
	v_mul_f32_e32 v144, v211, v146
	v_floor_f32_e32 v133, v133
	v_floor_f32_e32 v0, v0
	v_floor_f32_e32 v144, v144
	v_fma_f32 v133, v212, v146, -v133
	v_fma_f32 v0, v209, v146, -v0
	v_fma_f32 v147, v211, v146, -v144
	v_cos_f32_e32 v150, v133
	v_sin_f32_e32 v151, v133
	v_sin_f32_e32 v142, v0
	v_cos_f32_e32 v148, v147
	v_cos_f32_e32 v144, v0
	v_sin_f32_e32 v0, v147
	v_mov_b32_e32 v154, v135
	v_mov_b32_e32 v155, v137
	v_pk_mul_f32 v[150:151], v[150:151], v[154:155]
	v_pk_mul_f32 v[142:143], v[142:143], v[138:139]
	v_mul_f32_e32 v148, v148, v134
	v_mul_f32_e32 v152, v0, v136
	v_mov_b32_e32 v149, v150
	v_mov_b32_e32 v153, v151
	v_pk_fma_f32 v[142:143], v[144:145], v[140:141], v[142:143]
	v_pk_add_f32 v[144:145], v[148:149], v[152:153]

; __device__ __forceinline__ unsigned cvtpk(float lo, float hi) { f32x2 v = {lo, hi}; bf16x2_t b = __builtin_convertvector(v, bf16x2_t); return __builtin_bit_cast(unsigned, b); }
; __device__ __forceinline__ float fexp2(float x) { return __builtin_amdgcn_exp2f(x); }
; __device__ __forceinline__ u32x4 pack8(f32x4 a, f32x4 b) { u32x4 o; o.x = cvtpk(a[0], a[1]); o.y = cvtpk(a[2], a[3]); o.z = cvtpk(b[0], b[1]); o.w = cvtpk(b[2], b[3]); return o; }
;     template <int KIND> __device__ __forceinline__ void run(f32x4 (&acc)[2][2][4][2], const GUnit& u, int wr, int wc, int fr, int fq, int tid) const {
;     ...
;                 } else if (kind == EP_Q) {
;                     const float rs = __builtin_amdgcn_rsqf(ssq_q[row] * (1.f / 256.f) + EPS) * QSCALE;
;                     const int tok = row % TOK;
; #pragma unroll
;                     for (int bj = 0; bj < 2; ++bj) {
;                         const int head = 2 * pn + bj;
;                         f32x4 v0 = acc[ai][bj][m][0] * rs, v1 = acc[ai][bj][m][1] * rs;
;                         if (wc < 2) { *(u32x4*)(Qb + (size_t)row * 768 + head * 96 + wc * 32 + 8 * fq) = pack8(v0, v1); }
;                         else { f32x4 o = v0; const int g = 4 * (wc - 2) + fq;
;                             if (tok >= CTXL) { const int t = tok - CTXL; const int pos = (wc == 2) ? (t >> 6) : (t & 63);
; #pragma unroll
;                                 for (int j = 0; j < 4; ++j) { const float rv = (float)pos * (fexp2(-(float)(4 * (fq & 1) + j) * (13.287712379549449f / 8.f)) * 0.15915494309189535f);     const float fr_ = rv - floorf(rv); o[j] = v0[j] * __builtin_amdgcn_cosf(fr_) + v1[j] * __builtin_amdgcn_sinf(fr_); } }
;                             u32x2 pk; pk.x = cvtpk(o[0], o[1]); pk.y = cvtpk(o[2], o[3]);
;                             *(u32x2*)(Qb + (size_t)row * 768 + head * 96 + 64 + 4 * g) = pk; }
;                     }
.LBB0_546:
	v_add_u32_e32 v132, s50, v208
	v_readlane_b32 s16, v252, 13
	v_ashrrev_i32_e32 v133, 31, v132
	v_readlane_b32 s17, v252, 14
	s_mov_b32 s3, 0x38e38e39
	s_and_b64 vcc, exec, s[0:1]
	v_lshl_add_u64 v[130:131], v[132:133], 2, s[16:17]
	v_mov_b32_e32 v0, v220
	v_mul_hi_i32 v133, v132, s3
	v_lshrrev_b32_e32 v134, 31, v133
	v_ashrrev_i32_e32 v133, 9, v133
	v_add_u32_e32 v133, v133, v134
	s_movk_i32 s3, 0x600
	v_mul_i32_i24_e32 v133, 0x900, v133
	v_mad_i64_i32 v[130:131], s[16:17], v132, s3, 0
	v_sub_u32_e32 v132, v132, v133
	s_movk_i32 s3, 0xff
	v_add_u32_e32 v133, 0xffffff00, v132
	v_cmp_lt_i32_e64 s[44:45], s3, v132
	v_and_b32_e32 v132, 63, v132
	v_lshrrev_b32_e32 v133, 6, v133
	v_cndmask_b32_e64 v132, v132, v133, s[94:95]
	v_cvt_f32_u32_e32 v146, v132
	s_mov_b64 s[16:17], -1
	s_nop 0
	v_fmamk_f32 v0, v0, 0x3b800000, v202
	v_rsq_f32_e32 v0, v0
	s_nop 0
	v_mul_f32_e32 v132, 0x3e16c740, v0
	v_pk_mul_f32 v[134:135], v[40:41], v[132:133] op_sel_hi:[1,0]
	v_pk_mul_f32 v[140:141], v[38:39], v[132:133] op_sel_hi:[1,0]
	v_pk_mul_f32 v[136:137], v[36:37], v[132:133] op_sel_hi:[1,0]
	v_pk_mul_f32 v[138:139], v[34:35], v[132:133] op_sel_hi:[1,0]
	s_cbranch_vccnz .LBB0_550
	v_mov_b32_e32 v142, v140
	v_mov_b32_e32 v143, v141
	v_mov_b32_e32 v144, v134
	v_mov_b32_e32 v145, v135
	s_and_saveexec_b64 s[16:17], s[44:45]
	s_cbranch_execz .LBB0_549
	v_mul_f32_e32 v133, v210, v146
	v_floor_f32_e32 v133, v133
	v_fma_f32 v133, v210, v146, -v133
	v_sin_f32_e32 v143, v133
	v_cos_f32_e32 v145, v133
	v_mul_f32_e32 v133, v212, v146
	v_mul_f32_e32 v0, v209, v146
	v_mul_f32_e32 v144, v211, v146
	v_floor_f32_e32 v133, v133
	v_floor_f32_e32 v0, v0
	v_floor_f32_e32 v144, v144
	v_fma_f32 v133, v212, v146, -v133
	v_fma_f32 v0, v209, v146, -v0
	v_fma_f32 v147, v211, v146, -v144
	v_cos_f32_e32 v150, v133
	v_sin_f32_e32 v151, v133
	v_sin_f32_e32 v142, v0
	v_cos_f32_e32 v148, v147
	v_cos_f32_e32 v144, v0
	v_sin_f32_e32 v0, v147
	v_mov_b32_e32 v154, v135
	v_mov_b32_e32 v155, v137
	v_pk_mul_f32 v[150:151], v[150:151], v[154:155]
	v_pk_mul_f32 v[142:143], v[142:143], v[138:139]
	v_mul_f32_e32 v148, v148, v134
	v_mul_f32_e32 v152, v0, v136
	v_mov_b32_e32 v149, v150
	v_mov_b32_e32 v153, v151
	v_pk_fma_f32 v[142:143], v[144:145], v[140:141], v[142:143]
	v_pk_add_f32 v[144:145], v[148:149], v[152:153]

; #define LAS __attribute__((address_space(3)))
; __device__ __forceinline__ void pool_unit(LAS char* lds, int pm, int g, bf16_t* Z, const bf16_t* Wt  , const float* pscale, bool dry) {
;     ...
;     for (int k = 0; k < 4; ++k) { const int i = tid + 512 * k; *(LAS u32x4*)(U + (i >> 4) * PP + (i & 15) * 16) = wv[k]; }
;     __syncthreads();
;     f32x16 acc[4] = {};
; #pragma unroll
;     for (int s = 0; s < 8; ++s) {
;         const bf16x8 a = *(const LAS bf16x8*)(lds + (32 * wid + r32) * PP + (16 * s + 8 * hi) * 2);
; #pragma unroll
;         for (int n = 0; n < 4; ++n) {
;             const bf16x8 bw = *(const LAS bf16x8*)(U + (32 * n + r32) * PP + (16 * s + 8 * hi) * 2);
;             acc[n] = __builtin_amdgcn_mfma_f32_32x32x16_bf16(a, bw, acc[n], 0, 0, 0);
;         }
;     }
.LBB0_659:
	v_mad_u64_u32 v[18:19], s[0:1], v38, s58, v[46:47]
	s_waitcnt lgkmcnt(0)
	s_barrier
	s_waitcnt vmcnt(3)
	ds_write_b128 v18, v[6:9]
	v_mad_u64_u32 v[6:7], s[0:1], v40, s58, v[46:47]
	s_waitcnt vmcnt(2)
	ds_write_b128 v6, v[2:5]
	v_mad_u64_u32 v[2:3], s[0:1], v42, s58, v[46:47]
	s_waitcnt vmcnt(1)
	ds_write_b128 v2, v[14:17]
	v_mad_u64_u32 v[2:3], s[0:1], v44, s58, v[46:47]
	s_ashr_i32 s1, s17, 1
	s_waitcnt vmcnt(0)
	ds_write_b128 v2, v[10:13]
	s_and_b32 s0, s1, 0xffffffe0
	v_mov_b32_e32 v2, s1
	s_movk_i32 s1, 0xffe0
	v_bfe_u32 v0, v67, 5, 1
	v_bfi_b32 v2, s1, v2, v67
	v_mul_lo_u32 v2, v2, s58
	v_lshlrev_b32_e32 v69, 4, v0
	v_readlane_b32 s1, v254, 45
	v_and_b32_e32 v68, 31, v67
	v_add3_u32 v79, 0, v2, v69
	v_mov_b32_e32 v2, s1
	v_mad_u32_u24 v80, v68, s58, v2
	v_add_u32_e32 v10, v80, v69
	s_waitcnt lgkmcnt(0)
	s_barrier
	ds_read_b128 v[2:5], v10
	ds_read_b128 v[6:9], v79
	ds_read_b128 v[70:73], v79 offset:32
	s_waitcnt lgkmcnt(1)
	v_mfma_f32_32x32x16_bf16 v[50:65], v[6:9], v[2:5], 0
	ds_read_b128 v[2:5], v10 offset:8704
	v_or_b32_e32 v81, 32, v69
	v_add_u32_e32 v74, v80, v81
	ds_read_b128 v[74:77], v74
	v_mul_u32_u24_e32 v78, 0x110, v68
	v_add3_u32 v81, s1, v81, v78
	v_lshl_or_b32 v0, v0, 2, s0
	s_waitcnt lgkmcnt(1)
	v_mfma_f32_32x32x16_bf16 v[34:49], v[6:9], v[2:5], 0
	ds_read_b128 v[2:5], v10 offset:17408
	v_mul_lo_u32 v0, v0, s58
	s_movk_i32 s17, 0x1000
	s_waitcnt lgkmcnt(1)
	v_mfma_f32_32x32x16_bf16 v[50:65], v[70:73], v[74:77], v[50:65]
	ds_read_b128 v[74:77], v81 offset:8704
	s_waitcnt lgkmcnt(1)
	v_mfma_f32_32x32x16_bf16 v[18:33], v[6:9], v[2:5], 0
	ds_read_b128 v[2:5], v10 offset:26112
	s_waitcnt lgkmcnt(1)
	v_mfma_f32_32x32x16_bf16 v[34:49], v[70:73], v[74:77], v[34:49]
	ds_read_b128 v[74:77], v81 offset:17408
	s_waitcnt lgkmcnt(1)
	v_mfma_f32_32x32x16_bf16 v[2:17], v[6:9], v[2:5], 0
	s_waitcnt lgkmcnt(0)
	v_mfma_f32_32x32x16_bf16 v[18:33], v[70:73], v[74:77], v[18:33]
	ds_read_b128 v[74:77], v81 offset:26112
	v_or_b32_e32 v81, 64, v69
	s_waitcnt lgkmcnt(0)
	v_mfma_f32_32x32x16_bf16 v[2:17], v[70:73], v[74:77], v[2:17]
	ds_read_b128 v[70:73], v79 offset:64
	v_add_u32_e32 v74, v80, v81
	ds_read_b128 v[74:77], v74
	v_add3_u32 v81, s1, v81, v78
	s_waitcnt lgkmcnt(0)
	v_mfma_f32_32x32x16_bf16 v[50:65], v[70:73], v[74:77], v[50:65]
	ds_read_b128 v[74:77], v81 offset:8704
	s_waitcnt lgkmcnt(0)
	v_mfma_f32_32x32x16_bf16 v[34:49], v[70:73], v[74:77], v[34:49]
	ds_read_b128 v[74:77], v81 offset:17408
	s_waitcnt lgkmcnt(0)
	v_mfma_f32_32x32x16_bf16 v[18:33], v[70:73], v[74:77], v[18:33]
	ds_read_b128 v[74:77], v81 offset:26112
	v_or_b32_e32 v81, 0x60, v69
	s_waitcnt lgkmcnt(0)
	v_mfma_f32_32x32x16_bf16 v[2:17], v[70:73], v[74:77], v[2:17]
	ds_read_b128 v[70:73], v79 offset:96
	v_add_u32_e32 v74, v80, v81
	ds_read_b128 v[74:77], v74
	v_add3_u32 v81, s1, v81, v78
	s_waitcnt lgkmcnt(0)
	v_mfma_f32_32x32x16_bf16 v[50:65], v[70:73], v[74:77], v[50:65]
	ds_read_b128 v[74:77], v81 offset:8704
	s_waitcnt lgkmcnt(0)
	v_mfma_f32_32x32x16_bf16 v[34:49], v[70:73], v[74:77], v[34:49]
	ds_read_b128 v[74:77], v81 offset:17408
	s_waitcnt lgkmcnt(0)
	v_mfma_f32_32x32x16_bf16 v[18:33], v[70:73], v[74:77], v[18:33]
	ds_read_b128 v[74:77], v81 offset:26112
	v_or_b32_e32 v81, 0x80, v69
	s_waitcnt lgkmcnt(0)
	v_mfma_f32_32x32x16_bf16 v[2:17], v[70:73], v[74:77], v[2:17]
	ds_read_b128 v[70:73], v79 offset:128
	v_add_u32_e32 v74, v80, v81
	ds_read_b128 v[74:77], v74
	v_add3_u32 v81, s1, v81, v78
	s_waitcnt lgkmcnt(0)
	v_mfma_f32_32x32x16_bf16 v[50:65], v[70:73], v[74:77], v[50:65]
	ds_read_b128 v[74:77], v81 offset:8704
	s_waitcnt lgkmcnt(0)
	v_mfma_f32_32x32x16_bf16 v[34:49], v[70:73], v[74:77], v[34:49]
	ds_read_b128 v[74:77], v81 offset:17408
	s_waitcnt lgkmcnt(0)
	v_mfma_f32_32x32x16_bf16 v[18:33], v[70:73], v[74:77], v[18:33]
	ds_read_b128 v[74:77], v81 offset:26112
	v_or_b32_e32 v81, 0xa0, v69
	s_waitcnt lgkmcnt(0)
	v_mfma_f32_32x32x16_bf16 v[2:17], v[70:73], v[74:77], v[2:17]
	ds_read_b128 v[70:73], v79 offset:160
	v_add_u32_e32 v74, v80, v81
	ds_read_b128 v[74:77], v74
	v_add3_u32 v81, s1, v81, v78
	s_waitcnt lgkmcnt(0)
	v_mfma_f32_32x32x16_bf16 v[50:65], v[70:73], v[74:77], v[50:65]
	ds_read_b128 v[74:77], v81 offset:8704
	s_waitcnt lgkmcnt(0)
	v_mfma_f32_32x32x16_bf16 v[34:49], v[70:73], v[74:77], v[34:49]
	ds_read_b128 v[74:77], v81 offset:17408
	s_waitcnt lgkmcnt(0)
	v_mfma_f32_32x32x16_bf16 v[18:33], v[70:73], v[74:77], v[18:33]
	ds_read_b128 v[74:77], v81 offset:26112
	v_or_b32_e32 v81, 0xc0, v69
	v_or_b32_e32 v69, 0xe0, v69
	s_waitcnt lgkmcnt(0)
	v_mfma_f32_32x32x16_bf16 v[2:17], v[70:73], v[74:77], v[2:17]
	ds_read_b128 v[70:73], v79 offset:192
	v_add_u32_e32 v74, v80, v81
	ds_read_b128 v[74:77], v74
	v_add3_u32 v81, s1, v81, v78
	s_waitcnt lgkmcnt(0)
	v_mfma_f32_32x32x16_bf16 v[50:65], v[70:73], v[74:77], v[50:65]
	ds_read_b128 v[74:77], v81 offset:8704
	s_waitcnt lgkmcnt(0)
	v_mfma_f32_32x32x16_bf16 v[34:49], v[70:73], v[74:77], v[34:49]
	ds_read_b128 v[74:77], v81 offset:17408
	s_waitcnt lgkmcnt(0)
	v_mfma_f32_32x32x16_bf16 v[18:33], v[70:73], v[74:77], v[18:33]
	ds_read_b128 v[74:77], v81 offset:26112
	s_waitcnt lgkmcnt(0)
	v_mfma_f32_32x32x16_bf16 v[2:17], v[70:73], v[74:77], v[2:17]
	ds_read_b128 v[70:73], v79 offset:224
	v_add_u32_e32 v74, v80, v69
	ds_read_b128 v[74:77], v74
	v_add3_u32 v69, s1, v69, v78
	s_add_i32 s1, s0, s8
	s_lshl_b32 s8, s2, 1
	s_waitcnt lgkmcnt(0)
	v_mfma_f32_32x32x16_bf16 v[50:65], v[70:73], v[74:77], v[50:65]
	ds_read_b128 v[74:77], v69 offset:8704
	s_waitcnt lgkmcnt(0)
	v_mfma_f32_32x32x16_bf16 v[34:49], v[70:73], v[74:77], v[34:49]
	ds_read_b128 v[74:77], v69 offset:17408
	s_waitcnt lgkmcnt(0)
; #define LAS __attribute__((address_space(3)))
; __device__ __forceinline__ unsigned cvtpk(float lo, float hi) { f32x2 v = {lo, hi}; bf16x2_t b = __builtin_convertvector(v, bf16x2_t); return __builtin_bit_cast(unsigned, b); }
; __device__ __forceinline__ bf16_t f2bf(float f) { return (bf16_t)(cvtpk(f, 0.f) & 0xffffu); }
; __device__ __forceinline__ float bflo(unsigned u) { return __uint_as_float(u << 16); }
; __device__ __forceinline__ float bfhi(unsigned u) { return __uint_as_float(u & 0xffff0000u); }
; __device__ __forceinline__ int crow(int r, int hi) { return (r & 3) + 8 * (r >> 2) + 4 * hi; }
; __device__ __forceinline__ void pool_unit(LAS char* lds, int pm, int g, bf16_t* Z, const bf16_t* Wt  , const float* pscale, bool dry) {
;     ...
; #pragma unroll
;     for (int n = 0; n < 4; ++n) { const float sc = pscale[g * 128 + 32 * n + r32];
; #pragma unroll
;         for (int r = 0; r < 16; ++r) ((LAS bf16_t*)lds)[(32 * wid + crow(r, hi)) * (PP / 2) + 32 * n + r32] = f2bf(acc[n][r] * sc); }
;     asm volatile("s_waitcnt lgkmcnt(0)" ::: "memory");
; #pragma unroll
;     for (int i = 0; i < 8; ++i) { const int id = lane + 64 * i, row = id >> 4, ch = id & 15;
;         const u32x4 ov = *(const LAS u32x4*)(lds + (32 * wid + row) * PP + ch * 16);
;         bf16_t* yp = Z + (size_t)(pm * 256 + 32 * wid + row) * ZP + ZYP + g * 128 + ch * 8;
;         if (!dry) { const u32x4 gv = *(const u32x4*)yp; u32x4 w;
;             w.x = cvtpk(bflo(ov.x) * bflo(gv.x), bfhi(ov.x) * bfhi(gv.x)); w.y = cvtpk(bflo(ov.y) * bflo(gv.y), bfhi(ov.y) * bfhi(gv.y));
;             w.z = cvtpk(bflo(ov.z) * bflo(gv.z), bfhi(ov.z) * bfhi(gv.z)); w.w = cvtpk(bflo(ov.w) * bflo(gv.w), bfhi(ov.w) * bfhi(gv.w));
;             *(u32x4*)yp = w; } }
	v_mfma_f32_32x32x16_bf16 v[18:33], v[70:73], v[74:77], v[18:33]
	ds_read_b128 v[74:77], v69 offset:26112
	v_or_b32_e32 v69, s2, v68
	s_waitcnt lgkmcnt(0)
	v_mfma_f32_32x32x16_bf16 v[2:17], v[70:73], v[74:77], v[2:17]
	v_lshlrev_b32_e32 v70, 1, v68
	v_lshlrev_b32_e32 v68, 2, v69
	global_load_dword v69, v68, s[56:57]
	global_load_dword v162, v68, s[56:57] offset:128
	global_load_dword v163, v68, s[56:57] offset:256
	global_load_dword v164, v68, s[56:57] offset:384
	v_bfe_u32 v166, v67, 4, 2
	v_mov_b64_e32 v[168:169], s[88:89]
	v_mov_b32_e32 v170, v66
	v_mov_b32_e32 v171, 0
	v_or_b32_e32 v167, s1, v166
	v_mad_i64_i32 v[146:147], s[24:25], v167, s13, v[168:169]
	v_lshl_add_u64 v[146:147], v[146:147], 0, s[8:9]
	v_lshl_add_u64 v[146:147], v[146:147], 0, v[170:171]
	v_add_co_u32_e32 v146, vcc, s17, v146
	s_nop 1
	v_addc_co_u32_e32 v147, vcc, 0, v147, vcc
	global_load_dwordx4 v[114:117], v[146:147], off offset:1024
	v_or_b32_e32 v167, 4, v166
	v_or_b32_e32 v167, s1, v167
	v_mad_i64_i32 v[148:149], s[24:25], v167, s13, v[168:169]
	v_lshl_add_u64 v[148:149], v[148:149], 0, s[8:9]
	v_lshl_add_u64 v[148:149], v[148:149], 0, v[170:171]
	v_add_co_u32_e32 v148, vcc, s17, v148
	s_nop 1
	v_addc_co_u32_e32 v149, vcc, 0, v149, vcc
	global_load_dwordx4 v[118:121], v[148:149], off offset:1024
	v_or_b32_e32 v167, 8, v166
	v_or_b32_e32 v167, s1, v167
	v_mad_i64_i32 v[150:151], s[24:25], v167, s13, v[168:169]
	v_lshl_add_u64 v[150:151], v[150:151], 0, s[8:9]
	v_lshl_add_u64 v[150:151], v[150:151], 0, v[170:171]
	v_add_co_u32_e32 v150, vcc, s17, v150
	s_nop 1
	v_addc_co_u32_e32 v151, vcc, 0, v151, vcc
	global_load_dwordx4 v[122:125], v[150:151], off offset:1024
	v_or_b32_e32 v167, 12, v166
	v_or_b32_e32 v167, s1, v167
	v_mad_i64_i32 v[152:153], s[24:25], v167, s13, v[168:169]
	v_lshl_add_u64 v[152:153], v[152:153], 0, s[8:9]
	v_lshl_add_u64 v[152:153], v[152:153], 0, v[170:171]
	v_add_co_u32_e32 v152, vcc, s17, v152
	s_nop 1
	v_addc_co_u32_e32 v153, vcc, 0, v153, vcc
	global_load_dwordx4 v[126:129], v[152:153], off offset:1024
	v_or_b32_e32 v167, 16, v166
	v_or_b32_e32 v167, s1, v167
	v_mad_i64_i32 v[154:155], s[24:25], v167, s13, v[168:169]
	v_lshl_add_u64 v[154:155], v[154:155], 0, s[8:9]
	v_lshl_add_u64 v[154:155], v[154:155], 0, v[170:171]
	v_add_co_u32_e32 v154, vcc, s17, v154
	s_nop 1
	v_addc_co_u32_e32 v155, vcc, 0, v155, vcc
	global_load_dwordx4 v[130:133], v[154:155], off offset:1024
	v_or_b32_e32 v167, 20, v166
	v_or_b32_e32 v167, s1, v167
	v_mad_i64_i32 v[156:157], s[24:25], v167, s13, v[168:169]
	v_lshl_add_u64 v[156:157], v[156:157], 0, s[8:9]
	v_lshl_add_u64 v[156:157], v[156:157], 0, v[170:171]
	v_add_co_u32_e32 v156, vcc, s17, v156
	s_nop 1
	v_addc_co_u32_e32 v157, vcc, 0, v157, vcc
	global_load_dwordx4 v[134:137], v[156:157], off offset:1024
	v_or_b32_e32 v167, 24, v166
	v_or_b32_e32 v167, s1, v167
	v_mad_i64_i32 v[158:159], s[24:25], v167, s13, v[168:169]
	v_lshl_add_u64 v[158:159], v[158:159], 0, s[8:9]
	v_lshl_add_u64 v[158:159], v[158:159], 0, v[170:171]
	v_add_co_u32_e32 v158, vcc, s17, v158
	s_nop 1
	v_addc_co_u32_e32 v159, vcc, 0, v159, vcc
	global_load_dwordx4 v[138:141], v[158:159], off offset:1024
	v_or_b32_e32 v167, 28, v166
	v_or_b32_e32 v167, s1, v167
	v_mad_i64_i32 v[160:161], s[24:25], v167, s13, v[168:169]
	v_lshl_add_u64 v[160:161], v[160:161], 0, s[8:9]
	v_lshl_add_u64 v[160:161], v[160:161], 0, v[170:171]
	v_add_co_u32_e32 v160, vcc, s17, v160
	s_nop 1
	v_addc_co_u32_e32 v161, vcc, 0, v161, vcc
	global_load_dwordx4 v[142:145], v[160:161], off offset:1024
	v_add3_u32 v0, 0, v70, v0
	s_waitcnt vmcnt(11)
	v_mul_f32_e32 v50, v50, v69
	v_cvt_pk_bf16_f32 v50, v50, s0
	ds_write_b16 v0, v50
	v_mul_f32_e32 v50, v51, v69
	v_cvt_pk_bf16_f32 v50, v50, s0
	ds_write_b16 v0, v50 offset:272
	v_mul_f32_e32 v50, v52, v69
	v_cvt_pk_bf16_f32 v50, v50, s0
	ds_write_b16 v0, v50 offset:544
	v_mul_f32_e32 v50, v53, v69
	v_cvt_pk_bf16_f32 v50, v50, s0
	ds_write_b16 v0, v50 offset:816
	v_mul_f32_e32 v50, v54, v69
	v_cvt_pk_bf16_f32 v50, v50, s0
	ds_write_b16 v0, v50 offset:2176
	v_mul_f32_e32 v50, v55, v69
	v_cvt_pk_bf16_f32 v50, v50, s0
	ds_write_b16 v0, v50 offset:2448
	v_mul_f32_e32 v50, v56, v69
	v_cvt_pk_bf16_f32 v50, v50, s0
	ds_write_b16 v0, v50 offset:2720
	v_mul_f32_e32 v50, v57, v69
	v_cvt_pk_bf16_f32 v50, v50, s0
	ds_write_b16 v0, v50 offset:2992
	v_mul_f32_e32 v50, v58, v69
	v_cvt_pk_bf16_f32 v50, v50, s0
	ds_write_b16 v0, v50 offset:4352
	v_mul_f32_e32 v50, v59, v69
	v_cvt_pk_bf16_f32 v50, v50, s0
	ds_write_b16 v0, v50 offset:4624
	v_mul_f32_e32 v50, v60, v69
	v_cvt_pk_bf16_f32 v50, v50, s0
	ds_write_b16 v0, v50 offset:4896
	v_mul_f32_e32 v50, v61, v69
	v_cvt_pk_bf16_f32 v50, v50, s0
	ds_write_b16 v0, v50 offset:5168
	v_mul_f32_e32 v50, v62, v69
	v_cvt_pk_bf16_f32 v50, v50, s0
	ds_write_b16 v0, v50 offset:6528
	v_mul_f32_e32 v50, v63, v69
	v_cvt_pk_bf16_f32 v50, v50, s0
	ds_write_b16 v0, v50 offset:6800
	v_mul_f32_e32 v50, v64, v69
	v_cvt_pk_bf16_f32 v50, v50, s0
	ds_write_b16 v0, v50 offset:7072
	v_mul_f32_e32 v50, v65, v69
	v_cvt_pk_bf16_f32 v50, v50, s0
	ds_write_b16 v0, v50 offset:7344
	s_waitcnt vmcnt(10)
; #define LAS __attribute__((address_space(3)))
; __device__ __forceinline__ unsigned cvtpk(float lo, float hi) { f32x2 v = {lo, hi}; bf16x2_t b = __builtin_convertvector(v, bf16x2_t); return __builtin_bit_cast(unsigned, b); }
; __device__ __forceinline__ bf16_t f2bf(float f) { return (bf16_t)(cvtpk(f, 0.f) & 0xffffu); }
; __device__ __forceinline__ float bflo(unsigned u) { return __uint_as_float(u << 16); }
; __device__ __forceinline__ float bfhi(unsigned u) { return __uint_as_float(u & 0xffff0000u); }
; __device__ __forceinline__ int crow(int r, int hi) { return (r & 3) + 8 * (r >> 2) + 4 * hi; }
; __device__ __forceinline__ void pool_unit(LAS char* lds, int pm, int g, bf16_t* Z, const bf16_t* Wt  , const float* pscale, bool dry) {
;     ...
; #pragma unroll
;     for (int n = 0; n < 4; ++n) { const float sc = pscale[g * 128 + 32 * n + r32];
; #pragma unroll
;         for (int r = 0; r < 16; ++r) ((LAS bf16_t*)lds)[(32 * wid + crow(r, hi)) * (PP / 2) + 32 * n + r32] = f2bf(acc[n][r] * sc); }
;     asm volatile("s_waitcnt lgkmcnt(0)" ::: "memory");
; #pragma unroll
;     for (int i = 0; i < 8; ++i) { const int id = lane + 64 * i, row = id >> 4, ch = id & 15;
;         const u32x4 ov = *(const LAS u32x4*)(lds + (32 * wid + row) * PP + ch * 16);
;         bf16_t* yp = Z + (size_t)(pm * 256 + 32 * wid + row) * ZP + ZYP + g * 128 + ch * 8;
;         if (!dry) { const u32x4 gv = *(const u32x4*)yp; u32x4 w;
;             w.x = cvtpk(bflo(ov.x) * bflo(gv.x), bfhi(ov.x) * bfhi(gv.x)); w.y = cvtpk(bflo(ov.y) * bflo(gv.y), bfhi(ov.y) * bfhi(gv.y));
;             w.z = cvtpk(bflo(ov.z) * bflo(gv.z), bfhi(ov.z) * bfhi(gv.z)); w.w = cvtpk(bflo(ov.w) * bflo(gv.w), bfhi(ov.w) * bfhi(gv.w));
;             *(u32x4*)yp = w; } }
	v_mov_b32_e32 v50, v162
	v_mul_f32_e32 v34, v34, v50
	v_cvt_pk_bf16_f32 v34, v34, s0
	ds_write_b16 v0, v34 offset:64
	v_mul_f32_e32 v34, v35, v50
	v_cvt_pk_bf16_f32 v34, v34, s0
	ds_write_b16 v0, v34 offset:336
	v_mul_f32_e32 v34, v36, v50
	v_cvt_pk_bf16_f32 v34, v34, s0
	ds_write_b16 v0, v34 offset:608
	v_mul_f32_e32 v34, v37, v50
	v_cvt_pk_bf16_f32 v34, v34, s0
	ds_write_b16 v0, v34 offset:880
	v_mul_f32_e32 v34, v38, v50
	v_cvt_pk_bf16_f32 v34, v34, s0
	ds_write_b16 v0, v34 offset:2240
	v_mul_f32_e32 v34, v39, v50
	v_cvt_pk_bf16_f32 v34, v34, s0
	ds_write_b16 v0, v34 offset:2512
	v_mul_f32_e32 v34, v40, v50
	v_cvt_pk_bf16_f32 v34, v34, s0
	ds_write_b16 v0, v34 offset:2784
	v_mul_f32_e32 v34, v41, v50
	v_cvt_pk_bf16_f32 v34, v34, s0
	ds_write_b16 v0, v34 offset:3056
	v_mul_f32_e32 v34, v42, v50
	v_cvt_pk_bf16_f32 v34, v34, s0
	ds_write_b16 v0, v34 offset:4416
	v_mul_f32_e32 v34, v43, v50
	v_cvt_pk_bf16_f32 v34, v34, s0
	ds_write_b16 v0, v34 offset:4688
	v_mul_f32_e32 v34, v44, v50
	v_cvt_pk_bf16_f32 v34, v34, s0
	ds_write_b16 v0, v34 offset:4960
	v_mul_f32_e32 v34, v45, v50
	v_cvt_pk_bf16_f32 v34, v34, s0
	ds_write_b16 v0, v34 offset:5232
	v_mul_f32_e32 v34, v46, v50
	v_cvt_pk_bf16_f32 v34, v34, s0
	ds_write_b16 v0, v34 offset:6592
	v_mul_f32_e32 v34, v47, v50
	v_cvt_pk_bf16_f32 v34, v34, s0
	ds_write_b16 v0, v34 offset:6864
	v_mul_f32_e32 v34, v48, v50
	v_cvt_pk_bf16_f32 v34, v34, s0
	ds_write_b16 v0, v34 offset:7136
	v_mul_f32_e32 v34, v49, v50
	v_cvt_pk_bf16_f32 v34, v34, s0
	ds_write_b16 v0, v34 offset:7408
	s_waitcnt vmcnt(9)
	v_mov_b32_e32 v34, v163
	v_mul_f32_e32 v18, v18, v34
	v_cvt_pk_bf16_f32 v18, v18, s0
	ds_write_b16 v0, v18 offset:128
	v_mul_f32_e32 v18, v19, v34
	v_cvt_pk_bf16_f32 v18, v18, s0
	ds_write_b16 v0, v18 offset:400
	v_mul_f32_e32 v18, v20, v34
	v_cvt_pk_bf16_f32 v18, v18, s0
	ds_write_b16 v0, v18 offset:672
	v_mul_f32_e32 v18, v21, v34
	v_cvt_pk_bf16_f32 v18, v18, s0
	ds_write_b16 v0, v18 offset:944
	v_mul_f32_e32 v18, v22, v34
	v_cvt_pk_bf16_f32 v18, v18, s0
	ds_write_b16 v0, v18 offset:2304
	v_mul_f32_e32 v18, v23, v34
	v_cvt_pk_bf16_f32 v18, v18, s0
	ds_write_b16 v0, v18 offset:2576
	v_mul_f32_e32 v18, v24, v34
	v_cvt_pk_bf16_f32 v18, v18, s0
	ds_write_b16 v0, v18 offset:2848
	v_mul_f32_e32 v18, v25, v34
	v_cvt_pk_bf16_f32 v18, v18, s0
	ds_write_b16 v0, v18 offset:3120
	v_mul_f32_e32 v18, v26, v34
	v_cvt_pk_bf16_f32 v18, v18, s0
	ds_write_b16 v0, v18 offset:4480
	v_mul_f32_e32 v18, v27, v34
	v_cvt_pk_bf16_f32 v18, v18, s0
	ds_write_b16 v0, v18 offset:4752
	v_mul_f32_e32 v18, v28, v34
	v_cvt_pk_bf16_f32 v18, v18, s0
	ds_write_b16 v0, v18 offset:5024
	v_mul_f32_e32 v18, v29, v34
	v_cvt_pk_bf16_f32 v18, v18, s0
	ds_write_b16 v0, v18 offset:5296
	v_mul_f32_e32 v18, v30, v34
	v_cvt_pk_bf16_f32 v18, v18, s0
	ds_write_b16 v0, v18 offset:6656
	v_mul_f32_e32 v18, v31, v34
	v_cvt_pk_bf16_f32 v18, v18, s0
	ds_write_b16 v0, v18 offset:6928
	v_mul_f32_e32 v18, v32, v34
	v_cvt_pk_bf16_f32 v18, v18, s0
	ds_write_b16 v0, v18 offset:7200
	v_mul_f32_e32 v18, v33, v34
	v_cvt_pk_bf16_f32 v18, v18, s0
	ds_write_b16 v0, v18 offset:7472
	s_waitcnt vmcnt(8)
	v_mov_b32_e32 v18, v164
	v_mul_f32_e32 v2, v2, v18
	v_cvt_pk_bf16_f32 v2, v2, s0
	ds_write_b16 v0, v2 offset:192
	v_mul_f32_e32 v2, v3, v18
	v_cvt_pk_bf16_f32 v2, v2, s0
	ds_write_b16 v0, v2 offset:464
	v_mul_f32_e32 v2, v4, v18
	v_cvt_pk_bf16_f32 v2, v2, s0
	ds_write_b16 v0, v2 offset:736
	v_mul_f32_e32 v2, v5, v18
	v_cvt_pk_bf16_f32 v2, v2, s0
	ds_write_b16 v0, v2 offset:1008
	v_mul_f32_e32 v2, v6, v18
	v_cvt_pk_bf16_f32 v2, v2, s0
	ds_write_b16 v0, v2 offset:2368
	v_mul_f32_e32 v2, v7, v18
	v_cvt_pk_bf16_f32 v2, v2, s0
	ds_write_b16 v0, v2 offset:2640
	v_mul_f32_e32 v2, v8, v18
	v_cvt_pk_bf16_f32 v2, v2, s0
	ds_write_b16 v0, v2 offset:2912
	v_mul_f32_e32 v2, v9, v18
	v_cvt_pk_bf16_f32 v2, v2, s0
	ds_write_b16 v0, v2 offset:3184
	v_mul_f32_e32 v2, v10, v18
	v_cvt_pk_bf16_f32 v2, v2, s0
	ds_write_b16 v0, v2 offset:4544
	v_mul_f32_e32 v2, v11, v18
	v_cvt_pk_bf16_f32 v2, v2, s0
	ds_write_b16 v0, v2 offset:4816
	v_mul_f32_e32 v2, v12, v18
	v_cvt_pk_bf16_f32 v2, v2, s0
	ds_write_b16 v0, v2 offset:5088
	v_mul_f32_e32 v2, v13, v18
	v_cvt_pk_bf16_f32 v2, v2, s0
	ds_write_b16 v0, v2 offset:5360
	v_mul_f32_e32 v2, v14, v18
	v_cvt_pk_bf16_f32 v2, v2, s0
	ds_write_b16 v0, v2 offset:6720
	v_mul_f32_e32 v2, v15, v18
	v_cvt_pk_bf16_f32 v2, v2, s0
	ds_write_b16 v0, v2 offset:6992
	v_mul_f32_e32 v2, v16, v18
	v_cvt_pk_bf16_f32 v2, v2, s0
	ds_write_b16 v0, v2 offset:7264
	v_mul_f32_e32 v2, v17, v18
	v_cvt_pk_bf16_f32 v2, v2, s0
	v_bfe_u32 v4, v67, 4, 2
	ds_write_b16 v0, v2 offset:7536
	v_or_b32_e32 v5, s1, v4
	v_mov_b64_e32 v[2:3], s[88:89]
	v_mad_i64_i32 v[6:7], s[24:25], v5, s13, v[2:3]
	v_lshl_add_u64 v[6:7], v[6:7], 0, s[8:9]
	v_mov_b32_e32 v67, v1
	v_lshl_add_u64 v[10:11], v[6:7], 0, v[66:67]
	v_add_co_u32_e32 v14, vcc, s17, v10
	s_waitcnt lgkmcnt(0)
	v_add_u32_e32 v0, 0, v66
	s_nop 0
	v_addc_co_u32_e32 v15, vcc, 0, v11, vcc
	s_nop 0
	v_or_b32_e32 v5, s0, v4
	v_mad_u64_u32 v[6:7], s[2:3], v5, s58, v[0:1]
	ds_read_b128 v[6:9], v6
	v_or_b32_e32 v5, 4, v4
	s_waitcnt lgkmcnt(0)
	v_lshlrev_b32_e32 v16, 16, v6
	v_and_b32_e32 v17, 0xffff0000, v6
	s_waitcnt vmcnt(7)
; #define LAS __attribute__((address_space(3)))
; __device__ __forceinline__ unsigned cvtpk(float lo, float hi) { f32x2 v = {lo, hi}; bf16x2_t b = __builtin_convertvector(v, bf16x2_t); return __builtin_bit_cast(unsigned, b); }
; __device__ __forceinline__ float bflo(unsigned u) { return __uint_as_float(u << 16); }
; __device__ __forceinline__ float bfhi(unsigned u) { return __uint_as_float(u & 0xffff0000u); }
; __device__ __forceinline__ void pool_unit(LAS char* lds, int pm, int g, bf16_t* Z, const bf16_t* Wt  , const float* pscale, bool dry) {
;     ...
;     for (int i = 0; i < 8; ++i) { const int id = lane + 64 * i, row = id >> 4, ch = id & 15;
;         const u32x4 ov = *(const LAS u32x4*)(lds + (32 * wid + row) * PP + ch * 16);
;         bf16_t* yp = Z + (size_t)(pm * 256 + 32 * wid + row) * ZP + ZYP + g * 128 + ch * 8;
;         if (!dry) { const u32x4 gv = *(const u32x4*)yp; u32x4 w;
;             w.x = cvtpk(bflo(ov.x) * bflo(gv.x), bfhi(ov.x) * bfhi(gv.x)); w.y = cvtpk(bflo(ov.y) * bflo(gv.y), bfhi(ov.y) * bfhi(gv.y));
;             w.z = cvtpk(bflo(ov.z) * bflo(gv.z), bfhi(ov.z) * bfhi(gv.z)); w.w = cvtpk(bflo(ov.w) * bflo(gv.w), bfhi(ov.w) * bfhi(gv.w));
;             *(u32x4*)yp = w; } }
	v_mov_b64_e32 v[10:11], v[114:115]
	v_mov_b64_e32 v[12:13], v[116:117]
	v_lshlrev_b32_e32 v18, 16, v10
	v_and_b32_e32 v19, 0xffff0000, v10
	v_pk_mul_f32 v[16:17], v[16:17], v[18:19]
	v_lshlrev_b32_e32 v10, 16, v11
	v_cvt_pk_bf16_f32 v6, v16, v17
	v_lshlrev_b32_e32 v16, 16, v7
	v_and_b32_e32 v17, 0xffff0000, v7
	v_and_b32_e32 v11, 0xffff0000, v11
	v_pk_mul_f32 v[10:11], v[16:17], v[10:11]
	v_lshlrev_b32_e32 v16, 16, v12
	v_cvt_pk_bf16_f32 v7, v10, v11
	v_lshlrev_b32_e32 v10, 16, v8
	v_and_b32_e32 v11, 0xffff0000, v8
	v_and_b32_e32 v17, 0xffff0000, v12
	v_pk_mul_f32 v[10:11], v[10:11], v[16:17]
	v_lshlrev_b32_e32 v12, 16, v13
	v_cvt_pk_bf16_f32 v8, v10, v11
	v_lshlrev_b32_e32 v10, 16, v9
	v_and_b32_e32 v11, 0xffff0000, v9
	v_and_b32_e32 v13, 0xffff0000, v13
	v_pk_mul_f32 v[10:11], v[10:11], v[12:13]
	s_nop 0
	v_cvt_pk_bf16_f32 v9, v10, v11
	global_store_dwordx4 v[14:15], v[6:9], off offset:1024
	s_nop 1
	v_or_b32_e32 v6, s1, v5
	v_mad_i64_i32 v[6:7], s[2:3], v6, s13, v[2:3]
	v_lshl_add_u64 v[6:7], v[6:7], 0, s[8:9]
	v_lshl_add_u64 v[10:11], v[6:7], 0, v[66:67]
	v_add_co_u32_e32 v14, vcc, s17, v10
	v_or_b32_e32 v5, s0, v5
	s_nop 0
	v_addc_co_u32_e32 v15, vcc, 0, v11, vcc
	s_nop 0
	v_mad_u64_u32 v[6:7], s[2:3], v5, s58, v[0:1]
	ds_read_b128 v[6:9], v6
	v_or_b32_e32 v5, 8, v4
	s_waitcnt lgkmcnt(0)
	v_lshlrev_b32_e32 v16, 16, v6
	v_and_b32_e32 v17, 0xffff0000, v6
	s_waitcnt vmcnt(6)
	v_mov_b64_e32 v[10:11], v[118:119]
	v_mov_b64_e32 v[12:13], v[120:121]
	v_lshlrev_b32_e32 v18, 16, v10
	v_and_b32_e32 v19, 0xffff0000, v10
	v_pk_mul_f32 v[16:17], v[16:17], v[18:19]
	v_lshlrev_b32_e32 v10, 16, v11
	v_cvt_pk_bf16_f32 v6, v16, v17
	v_lshlrev_b32_e32 v16, 16, v7
	v_and_b32_e32 v17, 0xffff0000, v7
	v_and_b32_e32 v11, 0xffff0000, v11
	v_pk_mul_f32 v[10:11], v[16:17], v[10:11]
	v_lshlrev_b32_e32 v16, 16, v12
	v_cvt_pk_bf16_f32 v7, v10, v11
	v_lshlrev_b32_e32 v10, 16, v8
	v_and_b32_e32 v11, 0xffff0000, v8
	v_and_b32_e32 v17, 0xffff0000, v12
	v_pk_mul_f32 v[10:11], v[10:11], v[16:17]
	v_lshlrev_b32_e32 v12, 16, v13
	v_cvt_pk_bf16_f32 v8, v10, v11
	v_lshlrev_b32_e32 v10, 16, v9
	v_and_b32_e32 v11, 0xffff0000, v9
	v_and_b32_e32 v13, 0xffff0000, v13
	v_pk_mul_f32 v[10:11], v[10:11], v[12:13]
	s_nop 0
	v_cvt_pk_bf16_f32 v9, v10, v11
	global_store_dwordx4 v[14:15], v[6:9], off offset:1024
	s_nop 1
	v_or_b32_e32 v6, s1, v5
	v_mad_i64_i32 v[6:7], s[2:3], v6, s13, v[2:3]
	v_lshl_add_u64 v[6:7], v[6:7], 0, s[8:9]
	v_lshl_add_u64 v[10:11], v[6:7], 0, v[66:67]
	v_add_co_u32_e32 v14, vcc, s17, v10
	v_or_b32_e32 v5, s0, v5
	s_nop 0
	v_addc_co_u32_e32 v15, vcc, 0, v11, vcc
	s_nop 0
	v_mad_u64_u32 v[6:7], s[2:3], v5, s58, v[0:1]
	ds_read_b128 v[6:9], v6
	v_or_b32_e32 v5, 12, v4
	s_waitcnt lgkmcnt(0)
	v_lshlrev_b32_e32 v16, 16, v6
	v_and_b32_e32 v17, 0xffff0000, v6
	s_waitcnt vmcnt(5)
	v_mov_b64_e32 v[10:11], v[122:123]
	v_mov_b64_e32 v[12:13], v[124:125]
	v_lshlrev_b32_e32 v18, 16, v10
	v_and_b32_e32 v19, 0xffff0000, v10
	v_pk_mul_f32 v[16:17], v[16:17], v[18:19]
	v_lshlrev_b32_e32 v10, 16, v11
	v_cvt_pk_bf16_f32 v6, v16, v17
	v_lshlrev_b32_e32 v16, 16, v7
	v_and_b32_e32 v17, 0xffff0000, v7
	v_and_b32_e32 v11, 0xffff0000, v11
	v_pk_mul_f32 v[10:11], v[16:17], v[10:11]
	v_lshlrev_b32_e32 v16, 16, v12
	v_cvt_pk_bf16_f32 v7, v10, v11
	v_lshlrev_b32_e32 v10, 16, v8
	v_and_b32_e32 v11, 0xffff0000, v8
	v_and_b32_e32 v17, 0xffff0000, v12
	v_pk_mul_f32 v[10:11], v[10:11], v[16:17]
	v_lshlrev_b32_e32 v12, 16, v13
	v_cvt_pk_bf16_f32 v8, v10, v11
	v_lshlrev_b32_e32 v10, 16, v9
	v_and_b32_e32 v11, 0xffff0000, v9
	v_and_b32_e32 v13, 0xffff0000, v13
	v_pk_mul_f32 v[10:11], v[10:11], v[12:13]
	s_nop 0
	v_cvt_pk_bf16_f32 v9, v10, v11
	global_store_dwordx4 v[14:15], v[6:9], off offset:1024
	s_nop 1
	v_or_b32_e32 v6, s1, v5
	v_mad_i64_i32 v[6:7], s[2:3], v6, s13, v[2:3]
	v_lshl_add_u64 v[6:7], v[6:7], 0, s[8:9]
	v_lshl_add_u64 v[10:11], v[6:7], 0, v[66:67]
	v_add_co_u32_e32 v14, vcc, s17, v10
	v_or_b32_e32 v5, s0, v5
	s_nop 0
	v_addc_co_u32_e32 v15, vcc, 0, v11, vcc
	s_nop 0
	v_mad_u64_u32 v[6:7], s[2:3], v5, s58, v[0:1]
	ds_read_b128 v[6:9], v6
	v_or_b32_e32 v5, 16, v4
	s_waitcnt lgkmcnt(0)
	v_lshlrev_b32_e32 v16, 16, v6
	v_and_b32_e32 v17, 0xffff0000, v6
	s_waitcnt vmcnt(4)
	v_mov_b64_e32 v[10:11], v[126:127]
	v_mov_b64_e32 v[12:13], v[128:129]
	v_lshlrev_b32_e32 v18, 16, v10
	v_and_b32_e32 v19, 0xffff0000, v10
	v_pk_mul_f32 v[16:17], v[16:17], v[18:19]
	v_lshlrev_b32_e32 v10, 16, v11
	v_cvt_pk_bf16_f32 v6, v16, v17
	v_lshlrev_b32_e32 v16, 16, v7
	v_and_b32_e32 v17, 0xffff0000, v7
	v_and_b32_e32 v11, 0xffff0000, v11
	v_pk_mul_f32 v[10:11], v[16:17], v[10:11]
	v_lshlrev_b32_e32 v16, 16, v12
	v_cvt_pk_bf16_f32 v7, v10, v11
	v_lshlrev_b32_e32 v10, 16, v8
	v_and_b32_e32 v11, 0xffff0000, v8
	v_and_b32_e32 v17, 0xffff0000, v12
	v_pk_mul_f32 v[10:11], v[10:11], v[16:17]
	v_lshlrev_b32_e32 v12, 16, v13
	v_cvt_pk_bf16_f32 v8, v10, v11
	v_lshlrev_b32_e32 v10, 16, v9
	v_and_b32_e32 v11, 0xffff0000, v9
	v_and_b32_e32 v13, 0xffff0000, v13
	v_pk_mul_f32 v[10:11], v[10:11], v[12:13]
	s_nop 0
	v_cvt_pk_bf16_f32 v9, v10, v11
	global_store_dwordx4 v[14:15], v[6:9], off offset:1024
	s_nop 1
	v_or_b32_e32 v6, s1, v5
	v_mad_i64_i32 v[6:7], s[2:3], v6, s13, v[2:3]
	v_lshl_add_u64 v[6:7], v[6:7], 0, s[8:9]
	v_lshl_add_u64 v[10:11], v[6:7], 0, v[66:67]
	v_add_co_u32_e32 v14, vcc, s17, v10
	v_or_b32_e32 v5, s0, v5
	s_nop 0
	v_addc_co_u32_e32 v15, vcc, 0, v11, vcc
	s_nop 0
	v_mad_u64_u32 v[6:7], s[2:3], v5, s58, v[0:1]
	ds_read_b128 v[6:9], v6
	v_or_b32_e32 v5, 20, v4
	s_waitcnt lgkmcnt(0)
; #define LAS __attribute__((address_space(3)))
; __device__ __forceinline__ unsigned cvtpk(float lo, float hi) { f32x2 v = {lo, hi}; bf16x2_t b = __builtin_convertvector(v, bf16x2_t); return __builtin_bit_cast(unsigned, b); }
; __device__ __forceinline__ float bflo(unsigned u) { return __uint_as_float(u << 16); }
; __device__ __forceinline__ float bfhi(unsigned u) { return __uint_as_float(u & 0xffff0000u); }
; __device__ __forceinline__ void pool_unit(LAS char* lds, int pm, int g, bf16_t* Z, const bf16_t* Wt  , const float* pscale, bool dry) {
;     ...
;     for (int i = 0; i < 8; ++i) { const int id = lane + 64 * i, row = id >> 4, ch = id & 15;
;         const u32x4 ov = *(const LAS u32x4*)(lds + (32 * wid + row) * PP + ch * 16);
;         bf16_t* yp = Z + (size_t)(pm * 256 + 32 * wid + row) * ZP + ZYP + g * 128 + ch * 8;
;         if (!dry) { const u32x4 gv = *(const u32x4*)yp; u32x4 w;
;             w.x = cvtpk(bflo(ov.x) * bflo(gv.x), bfhi(ov.x) * bfhi(gv.x)); w.y = cvtpk(bflo(ov.y) * bflo(gv.y), bfhi(ov.y) * bfhi(gv.y));
;             w.z = cvtpk(bflo(ov.z) * bflo(gv.z), bfhi(ov.z) * bfhi(gv.z)); w.w = cvtpk(bflo(ov.w) * bflo(gv.w), bfhi(ov.w) * bfhi(gv.w));
;             *(u32x4*)yp = w; } }
	v_lshlrev_b32_e32 v16, 16, v6
	v_and_b32_e32 v17, 0xffff0000, v6
	s_waitcnt vmcnt(3)
	v_mov_b64_e32 v[10:11], v[130:131]
	v_mov_b64_e32 v[12:13], v[132:133]
	v_lshlrev_b32_e32 v18, 16, v10
	v_and_b32_e32 v19, 0xffff0000, v10
	v_pk_mul_f32 v[16:17], v[16:17], v[18:19]
	v_lshlrev_b32_e32 v10, 16, v11
	v_cvt_pk_bf16_f32 v6, v16, v17
	v_lshlrev_b32_e32 v16, 16, v7
	v_and_b32_e32 v17, 0xffff0000, v7
	v_and_b32_e32 v11, 0xffff0000, v11
	v_pk_mul_f32 v[10:11], v[16:17], v[10:11]
	v_lshlrev_b32_e32 v16, 16, v12
	v_cvt_pk_bf16_f32 v7, v10, v11
	v_lshlrev_b32_e32 v10, 16, v8
	v_and_b32_e32 v11, 0xffff0000, v8
	v_and_b32_e32 v17, 0xffff0000, v12
	v_pk_mul_f32 v[10:11], v[10:11], v[16:17]
	v_lshlrev_b32_e32 v12, 16, v13
	v_cvt_pk_bf16_f32 v8, v10, v11
	v_lshlrev_b32_e32 v10, 16, v9
	v_and_b32_e32 v11, 0xffff0000, v9
	v_and_b32_e32 v13, 0xffff0000, v13
	v_pk_mul_f32 v[10:11], v[10:11], v[12:13]
	s_nop 0
	v_cvt_pk_bf16_f32 v9, v10, v11
	global_store_dwordx4 v[14:15], v[6:9], off offset:1024
	s_nop 1
	v_or_b32_e32 v6, s1, v5
	v_mad_i64_i32 v[6:7], s[2:3], v6, s13, v[2:3]
	v_lshl_add_u64 v[6:7], v[6:7], 0, s[8:9]
	v_lshl_add_u64 v[10:11], v[6:7], 0, v[66:67]
	v_add_co_u32_e32 v14, vcc, s17, v10
	v_or_b32_e32 v5, s0, v5
	s_nop 0
	v_addc_co_u32_e32 v15, vcc, 0, v11, vcc
	s_nop 0
	v_mad_u64_u32 v[6:7], s[2:3], v5, s58, v[0:1]
	ds_read_b128 v[6:9], v6
	v_or_b32_e32 v5, 24, v4
	v_or_b32_e32 v4, 28, v4
	s_waitcnt lgkmcnt(0)
	v_lshlrev_b32_e32 v16, 16, v6
	v_and_b32_e32 v17, 0xffff0000, v6
	s_waitcnt vmcnt(2)
	v_mov_b64_e32 v[10:11], v[134:135]
	v_mov_b64_e32 v[12:13], v[136:137]
	v_lshlrev_b32_e32 v18, 16, v10
	v_and_b32_e32 v19, 0xffff0000, v10
	v_pk_mul_f32 v[16:17], v[16:17], v[18:19]
	v_lshlrev_b32_e32 v10, 16, v11
	v_cvt_pk_bf16_f32 v6, v16, v17
	v_lshlrev_b32_e32 v16, 16, v7
	v_and_b32_e32 v17, 0xffff0000, v7
	v_and_b32_e32 v11, 0xffff0000, v11
	v_pk_mul_f32 v[10:11], v[16:17], v[10:11]
	v_lshlrev_b32_e32 v16, 16, v12
	v_cvt_pk_bf16_f32 v7, v10, v11
	v_lshlrev_b32_e32 v10, 16, v8
	v_and_b32_e32 v11, 0xffff0000, v8
	v_and_b32_e32 v17, 0xffff0000, v12
	v_pk_mul_f32 v[10:11], v[10:11], v[16:17]
	v_lshlrev_b32_e32 v12, 16, v13
	v_cvt_pk_bf16_f32 v8, v10, v11
	v_lshlrev_b32_e32 v10, 16, v9
	v_and_b32_e32 v11, 0xffff0000, v9
	v_and_b32_e32 v13, 0xffff0000, v13
	v_pk_mul_f32 v[10:11], v[10:11], v[12:13]
	s_nop 0
	v_cvt_pk_bf16_f32 v9, v10, v11
	global_store_dwordx4 v[14:15], v[6:9], off offset:1024
	s_nop 1
	v_or_b32_e32 v6, s1, v5
	v_mad_i64_i32 v[6:7], s[2:3], v6, s13, v[2:3]
	v_lshl_add_u64 v[6:7], v[6:7], 0, s[8:9]
	v_lshl_add_u64 v[10:11], v[6:7], 0, v[66:67]
	v_add_co_u32_e32 v14, vcc, s17, v10
	v_or_b32_e32 v5, s0, v5
	s_nop 0
	v_addc_co_u32_e32 v15, vcc, 0, v11, vcc
	s_nop 0
	v_mad_u64_u32 v[6:7], s[2:3], v5, s58, v[0:1]
	ds_read_b128 v[6:9], v6
	v_or_b32_e32 v5, s1, v4
	v_mad_i64_i32 v[2:3], s[2:3], v5, s13, v[2:3]
	v_lshl_add_u64 v[2:3], v[2:3], 0, s[8:9]
	s_waitcnt lgkmcnt(0)
	v_lshlrev_b32_e32 v16, 16, v6
	v_and_b32_e32 v17, 0xffff0000, v6
	s_waitcnt vmcnt(1)
	v_mov_b64_e32 v[10:11], v[138:139]
	v_mov_b64_e32 v[12:13], v[140:141]
	v_lshlrev_b32_e32 v18, 16, v10
	v_and_b32_e32 v19, 0xffff0000, v10
	v_pk_mul_f32 v[16:17], v[16:17], v[18:19]
	v_lshlrev_b32_e32 v10, 16, v11
	v_cvt_pk_bf16_f32 v6, v16, v17
	v_lshlrev_b32_e32 v16, 16, v7
	v_and_b32_e32 v17, 0xffff0000, v7
	v_and_b32_e32 v11, 0xffff0000, v11
	v_pk_mul_f32 v[10:11], v[16:17], v[10:11]
	v_lshlrev_b32_e32 v16, 16, v12
	v_cvt_pk_bf16_f32 v7, v10, v11
	v_lshlrev_b32_e32 v10, 16, v8
	v_and_b32_e32 v11, 0xffff0000, v8
	v_and_b32_e32 v17, 0xffff0000, v12
	v_pk_mul_f32 v[10:11], v[10:11], v[16:17]
	v_lshlrev_b32_e32 v12, 16, v13
	v_cvt_pk_bf16_f32 v8, v10, v11
	v_lshlrev_b32_e32 v10, 16, v9
	v_and_b32_e32 v11, 0xffff0000, v9
	v_and_b32_e32 v13, 0xffff0000, v13
	v_pk_mul_f32 v[10:11], v[10:11], v[12:13]
	s_nop 0
	v_cvt_pk_bf16_f32 v9, v10, v11
	global_store_dwordx4 v[14:15], v[6:9], off offset:1024
	s_nop 1
	v_lshl_add_u64 v[6:7], v[2:3], 0, v[66:67]
	v_add_co_u32_e32 v10, vcc, s17, v6
	v_or_b32_e32 v2, s0, v4
	s_nop 0
	v_addc_co_u32_e32 v11, vcc, 0, v7, vcc
	s_nop 0
	v_mad_u64_u32 v[2:3], s[0:1], v2, s58, v[0:1]
	ds_read_b128 v[2:5], v2
	s_waitcnt lgkmcnt(0)
	v_lshlrev_b32_e32 v12, 16, v2
	v_and_b32_e32 v13, 0xffff0000, v2
	s_waitcnt vmcnt(0)
	v_mov_b64_e32 v[6:7], v[142:143]
	v_mov_b64_e32 v[8:9], v[144:145]
	v_lshlrev_b32_e32 v14, 16, v6
	v_and_b32_e32 v15, 0xffff0000, v6
	v_pk_mul_f32 v[12:13], v[12:13], v[14:15]
	v_lshlrev_b32_e32 v6, 16, v7
	v_cvt_pk_bf16_f32 v2, v12, v13
	v_lshlrev_b32_e32 v12, 16, v3
	v_and_b32_e32 v13, 0xffff0000, v3
	v_and_b32_e32 v7, 0xffff0000, v7
	v_pk_mul_f32 v[6:7], v[12:13], v[6:7]
	v_lshlrev_b32_e32 v12, 16, v8
	v_cvt_pk_bf16_f32 v3, v6, v7
	v_lshlrev_b32_e32 v6, 16, v4
	v_and_b32_e32 v7, 0xffff0000, v4
	v_and_b32_e32 v13, 0xffff0000, v8
	v_pk_mul_f32 v[6:7], v[6:7], v[12:13]
	v_lshlrev_b32_e32 v8, 16, v9
	v_cvt_pk_bf16_f32 v4, v6, v7
	v_lshlrev_b32_e32 v6, 16, v5
	v_and_b32_e32 v7, 0xffff0000, v5
	v_and_b32_e32 v9, 0xffff0000, v9
	v_pk_mul_f32 v[6:7], v[6:7], v[8:9]
	s_nop 0
	v_cvt_pk_bf16_f32 v5, v6, v7
	global_store_dwordx4 v[10:11], v[2:5], off offset:1024
	s_barrier
